# attention: K/V tile staging converted from register-staged global_load+ds_write to direct global_load_lds DMA (2-buffer ring, counted vmcnt(4) per half-trip)
# speedup vs baseline: 1.0099x; 1.0099x over previous
; __device__ __forceinline__ int opaque_tid() { int t = (int)threadIdx.x; asm volatile("" : "+v"(t)); return t; }
; __device__ __forceinline__ int v_st(int k, int c) { const int kk = (k & ~0xC) | ((k & 4) << 1) | ((k & 8) >> 1); return ((kk >> 3) * 4 + (c >> 5)) * 512 + ((kk & 7) * 32 + (c & 31)) * 2; }
; __device__ __forceinline__ int v_rd_base(int lane) { return ((lane & 3) << 3) | (((lane >> 2) & 3) << 6) | (((lane >> 4) & 1) << 5) | (((lane >> 5) & 1) << 8); }
; #define SLOAD(i, k0) do { sr_[i].vs0 = St::ld8(&Vh[(long)((k0) + sr) * LDK + sc]); sr_[i].vs1 = St::ld8(&Vh[(long)((k0) + 32 + sr) * LDK + sc]); \
;     sr_[i].ks0 = St::ld8(&Kh[(long)((k0) + sr) * LDK + sc]); sr_[i].ks1 = St::ld8(&Kh[(long)((k0) + 32 + sr) * LDK + sc]); } while (0)
; #define SWAIT() do { if constexpr (SDEPTH == 2) asm volatile("s_waitcnt vmcnt(4)" ::: "memory"); else asm volatile("s_waitcnt vmcnt(0)" ::: "memory"); } while (0)
; template <typename TQ>
; __device__ __forceinline__ void attn_dense_body(const TQ* __restrict__ Qb, const bf16* __restrict__ Kh, const bf16* __restrict__ Vh,
;                                                 unsigned short* __restrict__ Ob, int seq, char* lds) {
;     ...
;   const int tid = ::opaque_tid(), wid = tid >> 6, lane = tid & 63, r32 = lane & 31, hi = lane >> 5;
;   bf16* V_lds = (bf16*)lds; bf16* K_lds = (bf16*)(lds + 2 * SHM_V);
;   float* ws = (float*)(lds + 2 * SHM_V + 2 * SHM_K) + wid * 64; float* li_l = ws; float* al_l = ws + 32;
;   float m_reg = -1e30f, l_reg = 0; f32x16 o[4] = {}; bf16x8 qr[8];
;   const TQ* Qw = Qb + (long)(wid * QBLK + r32) * LDQ + hi * 8;
; #pragma unroll
;   for (int d0 = 0; d0 < 8; ++d0) qr[d0] = SQ::tobf(SQ::ld8(Qw + d0 * 16));
;   const int sr = tid >> 4, sc = (tid & 15) * 8, vst0 = v_st(sr, sc), vst1 = v_st(32 + sr, sc);
;   const int vb0 = (int)(uintptr_t)V_lds + v_rd_base(lane);
;   struct { typename St::T vs0, vs1, ks0, ks1; } sr_[SDEPTH];
;     ...
;   f32x16 pA0, pA1, pB0, pB1; float mnA, mnB, alA, alB; bf16x8 pa0, pa1, pa2, pa3; const int NT = seq / KVBLK;
;   constexpr int SE = 0, SO = SDEPTH - 1;
;   SLOAD(SE, 0); asm volatile("s_waitcnt vmcnt(0)" ::: "memory"); SWRITE(0, SE); __syncthreads();
;   qkt(pA0, pA1, K_lds, qr, r32, hi); partialSM(pA0, pA1, m_reg, mnA, alA);
;   SLOAD(SO, KVBLK); if constexpr (SDEPTH == 2) { if (2 < NT) SLOAD(SE, 2 * KVBLK); }
;   SWAIT(); SWRITE(1, SO); __syncthreads();
.LBB0_75:
	s_lshl_b64 s[40:41], s[0:1], 1
	v_readlane_b32 s0, v254, 41
	v_readlane_b32 s1, v254, 42
	s_add_u32 s46, s0, s40
	v_mov_b32_e32 v74, v211
	s_addc_u32 s47, s1, s41
	s_lshl_b64 s[0:1], s[38:39], 1
	s_add_u32 s38, s58, s0
	v_ashrrev_i32_e32 v16, 4, v74
	v_lshlrev_b32_e32 v22, 3, v74
	v_add_u32_e32 v18, 32, v16
	s_addc_u32 s39, s59, s1
	v_and_b32_e32 v176, 0x78, v22
	v_ashrrev_i32_e32 v17, 31, v16
	v_ashrrev_i32_e32 v19, 31, v18
	s_add_u32 s42, s24, s0
	v_lshlrev_b32_e32 v23, 1, v176
	v_lshlrev_b64 v[48:49], 8, v[16:17]
	v_lshlrev_b64 v[8:9], 8, v[18:19]
	s_addc_u32 s43, s25, s1
	s_mov_b64 s[6:7], s[38:39]
	s_mov_b64 s[68:69], s[42:43]
	v_or_b32_e32 v50, v48, v23
	v_mov_b32_e32 v51, v49
	v_or_b32_e32 v8, v8, v23
	v_ashrrev_i32_e32 v183, 6, v74
	s_waitcnt lgkmcnt(0)
	v_lshl_add_u64 v[0:1], s[42:43], 0, v[50:51]
	v_lshl_add_u64 v[4:5], s[42:43], 0, v[8:9]
	v_lshl_add_u64 v[10:11], s[38:39], 0, v[50:51]
	v_lshl_add_u64 v[12:13], s[38:39], 0, v[8:9]
	v_and_b32_e32 v179, 31, v74
	v_lshlrev_b32_e32 v178, 5, v183
	global_load_dwordx4 v[0:3], v[0:1], off
	s_nop 0
	global_load_dwordx4 v[4:7], v[4:5], off
	s_nop 0
	global_load_dwordx4 v[8:11], v[10:11], off
	s_nop 0
	global_load_dwordx4 v[12:15], v[12:13], off
	v_or_b32_e32 v20, v178, v179
	v_ashrrev_i32_e32 v21, 31, v20
	v_bfe_u32 v182, v74, 5, 1
	v_lshlrev_b64 v[20:21], 11, v[20:21]
	v_lshl_add_u64 v[20:21], s[46:47], 0, v[20:21]
	v_lshlrev_b32_e32 v208, 4, v182
	v_lshl_add_u64 v[20:21], v[20:21], 0, v[208:209]
	global_load_dwordx4 v[112:115], v[20:21], off
	global_load_dwordx4 v[108:111], v[20:21], off offset:32
	global_load_dwordx4 v[120:123], v[20:21], off offset:64
	global_load_dwordx4 v[124:127], v[20:21], off offset:96
	global_load_dwordx4 v[116:119], v[20:21], off offset:128
	global_load_dwordx4 v[104:107], v[20:21], off offset:160
	global_load_dwordx4 v[100:103], v[20:21], off offset:192
	global_load_dwordx4 v[96:99], v[20:21], off offset:224
	v_and_b32_e32 v19, 0xfffff0, v16
	v_lshlrev_b32_e32 v24, 1, v16
	v_lshrrev_b32_e32 v25, 1, v16
	v_and_b32_e32 v26, 3, v16
	v_and_or_b32 v19, v24, 8, v19
	v_and_or_b32 v24, v25, 4, v26
	v_and_b32_e32 v25, 0xfffff0, v18
	v_lshlrev_b32_e32 v26, 1, v18
	v_and_b32_e32 v17, 0x70, v74
	v_bfe_u32 v22, v22, 5, 2
	v_lshlrev_b32_e32 v16, 8, v16
	v_lshlrev_b32_e32 v18, 8, v18
	v_lshrrev_b32_e32 v19, 1, v19
	v_and_or_b32 v25, v26, 8, v25
	v_lshlrev_b32_e32 v52, 4, v74
	v_bitop3_b32 v16, v23, v16, v17 bitop3:0xde
	v_bitop3_b32 v17, v23, v18, v17 bitop3:0xde
	v_or_b32_e32 v18, v19, v22
	v_lshrrev_b32_e32 v19, 1, v25
	v_lshlrev_b32_e32 v68, 8, v179
	v_and_b32_e32 v69, 0x70, v52
	v_lshlrev_b32_e32 v24, 6, v24
	v_and_b32_e32 v28, 48, v23
	v_add_u32_e32 v189, 0, v16
	v_add_u32_e32 v190, 0, v17
	v_lshlrev_b32_e32 v16, 9, v18
	v_or_b32_e32 v17, v19, v22
	v_bitop3_b32 v27, v208, v68, v69 bitop3:0xde
	v_or3_b32 v16, v16, v24, v28
	v_lshlrev_b32_e32 v17, 9, v17
	v_or3_b32 v17, v17, v24, v28
	v_add_u32_e32 v191, 0, v16
	v_add_u32_e32 v193, 0, v27
	s_waitcnt vmcnt(0)
	v_add_u32_e32 v192, 0, v17
	s_mov_b64 s[28:29], 0x4000
	s_add_i32 s3, 0, 0x10000
	v_and_b32_e32 v71, 0xc0, v52
	v_and_b32_e32 v177, 63, v74
	v_lshlrev_b32_e32 v70, 3, v177
	s_mov_b32 s4, 0x42b504f3
	s_cmp_lg_u32 0, -1
	s_mov_b32 s72, s73
	s_mov_b32 s74, s73
	s_mov_b32 s75, s73
	s_waitcnt vmcnt(0)
	ds_write_b128 v191, v[0:3]
	s_waitcnt vmcnt(10)
	ds_write_b128 v192, v[4:7]
	s_waitcnt vmcnt(9)
	ds_write_b128 v189, v[8:11] offset:32768
	s_waitcnt vmcnt(8)
	ds_write_b128 v190, v[12:15] offset:32768
	s_waitcnt lgkmcnt(0)
	s_barrier
	ds_read_b128 v[0:3], v193 offset:32768
	ds_read_b128 v[4:7], v193 offset:40960
	s_waitcnt vmcnt(7) lgkmcnt(1)
	v_mfma_f32_32x32x16_bf16 v[16:31], v[0:3], v[112:115], 0
	v_or_b32_e32 v0, 32, v208
	v_bitop3_b32 v0, v0, v68, v69 bitop3:0xde
	v_add_u32_e32 v198, 0, v0
	v_and_b32_e32 v12, 0x3fffffc0, v74
	v_lshl_add_u64 v[8:9], v[50:51], 0, s[28:29]
	s_mov_b64 s[28:29], 0x6000
	v_lshl_add_u64 v[10:11], v[50:51], 0, s[28:29]
	s_waitcnt lgkmcnt(0)
	v_mfma_f32_32x32x16_bf16 v[32:47], v[4:7], v[112:115], 0
	ds_read_b128 v[0:3], v198 offset:32768
	ds_read_b128 v[4:7], v198 offset:40960
	v_lshl_add_u32 v184, v12, 2, s3
	v_lshl_add_u64 v[12:13], s[42:43], 0, v[8:9]
	v_lshl_add_u64 v[14:15], s[42:43], 0, v[10:11]
	s_mov_b64 s[28:29], 0x8000
	s_cselect_b32 s3, 0, 0
	s_mov_b32 s76, s73
	s_waitcnt vmcnt(6) lgkmcnt(1)
	v_mfma_f32_32x32x16_bf16 v[16:31], v[0:3], v[108:111], v[16:31]
	v_or_b32_e32 v0, 64, v208
	v_bitop3_b32 v0, v0, v68, v69 bitop3:0xde
	v_add_u32_e32 v197, 0, v0
	s_mov_b32 s77, s73
	s_mov_b32 s78, s73
	s_mov_b32 s79, s73
	s_mov_b32 s80, s73
	s_waitcnt lgkmcnt(0)
	v_mfma_f32_32x32x16_bf16 v[32:47], v[4:7], v[108:111], v[32:47]
	ds_read_b128 v[0:3], v197 offset:32768
	ds_read_b128 v[4:7], v197 offset:40960
	s_mov_b32 s81, s73
	s_mov_b32 s82, s73
	s_mov_b32 s83, s73
	s_mov_b32 s84, s73
	s_mov_b32 s85, s73
	s_mov_b32 s86, s73
	s_waitcnt vmcnt(5) lgkmcnt(1)
	v_mfma_f32_32x32x16_bf16 v[16:31], v[0:3], v[120:123], v[16:31]
	v_or_b32_e32 v0, 0x60, v208
	v_bitop3_b32 v0, v0, v68, v69 bitop3:0xde
	v_add_u32_e32 v196, 0, v0
	s_mov_b32 s87, s73
	v_lshl_add_u32 v185, v179, 2, v184
	v_mov_b32_e32 v186, 0
	s_waitcnt lgkmcnt(0)
	v_mfma_f32_32x32x16_bf16 v[32:47], v[4:7], v[120:123], v[32:47]
	ds_read_b128 v[0:3], v196 offset:32768
	ds_read_b128 v[4:7], v196 offset:40960
	s_waitcnt vmcnt(4) lgkmcnt(1)
	v_mfma_f32_32x32x16_bf16 v[16:31], v[0:3], v[124:127], v[16:31]
	v_or_b32_e32 v0, 0x80, v208
	v_bitop3_b32 v0, v0, v68, v69 bitop3:0xde
	v_add_u32_e32 v194, 0, v0
	ds_read_b128 v[0:3], v194 offset:32768
	s_waitcnt lgkmcnt(1)
	v_mfma_f32_32x32x16_bf16 v[32:47], v[4:7], v[124:127], v[32:47]
	ds_read_b128 v[4:7], v194 offset:40960
	s_waitcnt vmcnt(3) lgkmcnt(1)
; #define SLOAD(i, k0) do { sr_[i].vs0 = St::ld8(&Vh[(long)((k0) + sr) * LDK + sc]); sr_[i].vs1 = St::ld8(&Vh[(long)((k0) + 32 + sr) * LDK + sc]); \
;     sr_[i].ks0 = St::ld8(&Kh[(long)((k0) + sr) * LDK + sc]); sr_[i].ks1 = St::ld8(&Kh[(long)((k0) + 32 + sr) * LDK + sc]); } while (0)
; #define SWAIT() do { if constexpr (SDEPTH == 2) asm volatile("s_waitcnt vmcnt(4)" ::: "memory"); else asm volatile("s_waitcnt vmcnt(0)" ::: "memory"); } while (0)
; __device__ __forceinline__ void partialSM(f32x16& p0, f32x16& p1, float& m_reg, float& mn, float& alpha) {
;   constexpr float C = SCALE * 1.4426950408889634f;
;   float pmax = p0[0]; for (int r = 1; r < 16; ++r) pmax = fmaxf(pmax, p0[r]); for (int r = 0; r < 16; ++r) pmax = fmaxf(pmax, p1[r]);
;   { auto rr = __builtin_amdgcn_permlane32_swap(__float_as_uint(pmax), __float_as_uint(pmax), false, false);
;     pmax = fmaxf(__uint_as_float(rr[0]), __uint_as_float(rr[1])); }
;   if (__builtin_expect(__all(pmax - m_reg <= THR / SCALE), 1)) { mn = m_reg; alpha = 1.f; }
;   else { mn = fmaxf(m_reg, pmax); alpha = __builtin_amdgcn_exp2f((m_reg - mn) * C); m_reg = mn; }
;   float mnC = -mn * C;
;   for (int r = 0; r < 16; ++r) p0[r] = fmaf(p0[r], C, mnC); for (int r = 0; r < 16; ++r) p1[r] = fmaf(p1[r], C, mnC);
;   for (int r = 0; r < 16; ++r) p0[r] = __builtin_amdgcn_exp2f(p0[r]);
; template <typename TQ>
; __device__ __forceinline__ void attn_dense_body(const TQ* __restrict__ Qb, const bf16* __restrict__ Kh, const bf16* __restrict__ Vh,
;                                                 unsigned short* __restrict__ Ob, int seq, char* lds) {
;     ...
;   SLOAD(SE, 0); asm volatile("s_waitcnt vmcnt(0)" ::: "memory"); SWRITE(0, SE); __syncthreads();
;   qkt(pA0, pA1, K_lds, qr, r32, hi); partialSM(pA0, pA1, m_reg, mnA, alA);
;   SLOAD(SO, KVBLK); if constexpr (SDEPTH == 2) { if (2 < NT) SLOAD(SE, 2 * KVBLK); }
;   SWAIT(); SWRITE(1, SO); __syncthreads();
	v_mfma_f32_32x32x16_bf16 v[16:31], v[0:3], v[116:119], v[16:31]
	v_or_b32_e32 v0, 0xa0, v208
	v_bitop3_b32 v0, v0, v68, v69 bitop3:0xde
	v_add_u32_e32 v195, 0, v0
	ds_read_b128 v[0:3], v195 offset:32768
	s_waitcnt lgkmcnt(1)
	v_mfma_f32_32x32x16_bf16 v[32:47], v[4:7], v[116:119], v[32:47]
	ds_read_b128 v[4:7], v195 offset:40960
	global_load_dwordx4 v[52:55], v[12:13], off
	global_load_dwordx4 v[56:59], v[14:15], off
	s_waitcnt vmcnt(4) lgkmcnt(1)
	v_mfma_f32_32x32x16_bf16 v[16:31], v[0:3], v[104:107], v[16:31]
	v_lshl_add_u64 v[0:1], s[38:39], 0, v[8:9]
	v_lshl_add_u64 v[2:3], s[38:39], 0, v[10:11]
	global_load_dwordx4 v[60:63], v[0:1], off
	global_load_dwordx4 v[64:67], v[2:3], off
	v_or_b32_e32 v0, 0xc0, v208
	v_bitop3_b32 v0, v0, v68, v69 bitop3:0xde
	v_add_u32_e32 v200, 0, v0
	ds_read_b128 v[0:3], v200 offset:32768
	v_lshlrev_b32_e32 v9, 1, v74
	v_and_or_b32 v8, v70, 24, v71
	s_waitcnt lgkmcnt(1)
	v_mfma_f32_32x32x16_bf16 v[32:47], v[4:7], v[104:107], v[32:47]
	v_and_b32_e32 v4, 32, v9
	v_and_b32_e32 v5, 0x100, v70
	v_or3_b32 v75, v8, v4, v5
	ds_read_b128 v[4:7], v200 offset:40960
	v_add_u32_e32 v188, s3, v75
	s_waitcnt vmcnt(5) lgkmcnt(1)
	v_mfma_f32_32x32x16_bf16 v[16:31], v[0:3], v[100:103], v[16:31]
	v_or_b32_e32 v0, 0xe0, v208
	v_bitop3_b32 v0, v0, v68, v69 bitop3:0xde
	v_add_u32_e32 v199, 0, v0
	ds_read_b128 v[0:3], v199 offset:32768
	ds_read_b128 v[68:71], v199 offset:40960
	s_waitcnt lgkmcnt(2)
	v_mfma_f32_32x32x16_bf16 v[32:47], v[4:7], v[100:103], v[32:47]
	s_waitcnt vmcnt(4) lgkmcnt(1)
	v_mfma_f32_32x32x16_bf16 v[16:31], v[0:3], v[96:99], v[16:31]
	v_mov_b64_e32 v[0:1], s[72:73]
	v_mov_b64_e32 v[14:15], s[86:87]
	v_mov_b64_e32 v[2:3], s[74:75]
	v_mov_b64_e32 v[4:5], s[76:77]
	v_mov_b64_e32 v[6:7], s[78:79]
	v_mov_b64_e32 v[8:9], s[80:81]
	v_mov_b64_e32 v[10:11], s[82:83]
	s_waitcnt lgkmcnt(0)
	v_mfma_f32_32x32x16_bf16 v[32:47], v[68:71], v[96:99], v[32:47]
	s_nop 2
	v_max_f32_e32 v68, v17, v17
	v_max_f32_e32 v69, v16, v16
	v_max_f32_e32 v68, v69, v68
	v_max3_f32 v68, v68, v18, v19
	v_max3_f32 v68, v68, v20, v21
	v_max3_f32 v68, v68, v22, v23
	v_max3_f32 v68, v68, v24, v25
	v_max3_f32 v68, v68, v26, v27
	v_max3_f32 v68, v68, v28, v29
	v_max3_f32 v68, v68, v30, v31
	v_max3_f32 v68, v68, v32, v33
	v_max3_f32 v68, v68, v34, v35
	v_max3_f32 v68, v68, v36, v37
	v_max3_f32 v68, v68, v38, v39
	v_max3_f32 v68, v68, v40, v41
	v_max3_f32 v68, v68, v42, v43
	v_max3_f32 v76, v68, v44, v45
	v_lshl_add_u64 v[68:69], v[50:51], 0, s[28:29]
	s_mov_b64 s[28:29], 0xa000
	v_lshl_add_u64 v[70:71], s[42:43], 0, v[68:69]
	v_lshl_add_u64 v[50:51], v[50:51], 0, s[28:29]
	v_lshl_add_u64 v[68:69], s[38:39], 0, v[68:69]
	v_lshl_add_u64 v[72:73], s[42:43], 0, v[50:51]
	global_load_dwordx4 v[128:131], v[70:71], off
	global_load_dwordx4 v[136:139], v[72:73], off
	v_lshl_add_u64 v[50:51], s[38:39], 0, v[50:51]
	global_load_dwordx4 v[132:135], v[68:69], off
	global_load_dwordx4 v[140:143], v[50:51], off
	v_max3_f32 v50, v76, v46, v47
	v_mov_b32_e32 v51, v50
	s_nop 1
	v_permlane32_swap_b32_e32 v50, v51
	v_max_f32_e32 v51, v51, v51
	v_max_f32_e32 v50, v50, v50
	v_max_f32_e32 v50, v50, v51
	v_add_f32_e32 v51, 0x7149f2ca, v50
	v_max_f32_e32 v50, 0xf149f2ca, v50
	v_cmp_ge_f32_e32 vcc, s4, v51
	v_sub_f32_e32 v51, 0xf149f2ca, v50
	v_mul_f32_e32 v51, 0x3e0293ee, v51
	v_exp_f32_e32 v51, v51
	s_cmp_eq_u64 vcc, exec
	s_cselect_b64 vcc, -1, 0
	s_addk_i32 s3, 0x4000
	v_cndmask_b32_e64 v201, v51, 1.0, vcc
	v_mov_b32_e32 v51, 0xf149f2ca
	v_cndmask_b32_e32 v168, v50, v51, vcc
	v_mul_f32_e32 v50, 0xbe0293ee, v168
	v_fmamk_f32 v16, v16, 0x3e0293ee, v50
	v_exp_f32_e32 v161, v16
	v_fmamk_f32 v16, v17, 0x3e0293ee, v50
	v_exp_f32_e32 v175, v16
	v_fmamk_f32 v16, v18, 0x3e0293ee, v50
	v_exp_f32_e32 v162, v16
	v_fmamk_f32 v16, v19, 0x3e0293ee, v50
	v_exp_f32_e32 v205, v16
	v_fmamk_f32 v16, v20, 0x3e0293ee, v50
	v_exp_f32_e32 v174, v16
	v_fmamk_f32 v16, v21, 0x3e0293ee, v50
	v_exp_f32_e32 v214, v16
	v_fmamk_f32 v16, v22, 0x3e0293ee, v50
	v_exp_f32_e32 v163, v16
	v_fmamk_f32 v16, v23, 0x3e0293ee, v50
	v_exp_f32_e32 v173, v16
	v_fmamk_f32 v16, v24, 0x3e0293ee, v50
	v_exp_f32_e32 v164, v16
	v_fmamk_f32 v16, v25, 0x3e0293ee, v50
	v_exp_f32_e32 v171, v16
	v_fmamk_f32 v16, v26, 0x3e0293ee, v50
	v_exp_f32_e32 v165, v16
	v_fmamk_f32 v16, v27, 0x3e0293ee, v50
	v_exp_f32_e32 v172, v16
	v_fmamk_f32 v16, v28, 0x3e0293ee, v50
	v_exp_f32_e32 v166, v16
	v_fmamk_f32 v16, v29, 0x3e0293ee, v50
	v_pk_fma_f32 v[144:145], v[46:47], s[22:23], v[50:51] op_sel_hi:[1,0,0]
	v_pk_fma_f32 v[150:151], v[44:45], s[22:23], v[50:51] op_sel_hi:[1,0,0]
	v_pk_fma_f32 v[154:155], v[42:43], s[22:23], v[50:51] op_sel_hi:[1,0,0]
	v_pk_fma_f32 v[146:147], v[40:41], s[22:23], v[50:51] op_sel_hi:[1,0,0]
	v_pk_fma_f32 v[148:149], v[38:39], s[22:23], v[50:51] op_sel_hi:[1,0,0]
	v_pk_fma_f32 v[152:153], v[36:37], s[22:23], v[50:51] op_sel_hi:[1,0,0]
	v_pk_fma_f32 v[156:157], v[34:35], s[22:23], v[50:51] op_sel_hi:[1,0,0]
	v_pk_fma_f32 v[158:159], v[32:33], s[22:23], v[50:51] op_sel_hi:[1,0,0]
	v_exp_f32_e32 v169, v16
	v_fmamk_f32 v16, v30, 0x3e0293ee, v50
	v_fmac_f32_e32 v50, 0x3e0293ee, v31
	v_add_u32_e32 v187, s3, v75
	v_readlane_b32 s3, v253, 29
	v_exp_f32_e32 v167, v16
	v_exp_f32_e32 v170, v50
	v_and_b32_e32 v16, 15, v74
	s_add_u32 s0, s3, s0
	v_readlane_b32 s3, v253, 30
	s_waitcnt vmcnt(4)
	v_lshl_or_b32 v48, v16, 4, v48
	s_addc_u32 s1, s3, s1
	v_mov_b64_e32 v[12:13], s[84:85]
	s_waitcnt vmcnt(7)
	ds_write_b128 v191, v[52:55] offset:16384
	s_waitcnt vmcnt(6)
	ds_write_b128 v192, v[56:59] offset:16384
	s_waitcnt vmcnt(5)
	ds_write_b128 v189, v[60:63] offset:49152
	s_waitcnt vmcnt(4)
	ds_write_b128 v190, v[64:67] offset:49152
	v_lshl_add_u64 v[180:181], s[0:1], 0, v[48:49]
	v_mov_b64_e32 v[62:63], v[14:15]
	v_mov_b64_e32 v[46:47], v[14:15]
	v_mov_b64_e32 v[30:31], v[14:15]
	v_readlane_b32 s84, v252, 4
	v_cmp_gt_u32_e64 s[38:39], 32, v177
	v_mov_b64_e32 v[60:61], v[12:13]
	v_mov_b64_e32 v[58:59], v[10:11]
	v_mov_b64_e32 v[56:57], v[8:9]
	v_mov_b64_e32 v[54:55], v[6:7]
	v_mov_b64_e32 v[52:53], v[4:5]
	v_mov_b64_e32 v[50:51], v[2:3]
	v_mov_b64_e32 v[48:49], v[0:1]
	v_mov_b64_e32 v[44:45], v[12:13]
	v_mov_b64_e32 v[42:43], v[10:11]
	v_mov_b64_e32 v[40:41], v[8:9]
	v_mov_b64_e32 v[38:39], v[6:7]
	v_mov_b64_e32 v[36:37], v[4:5]
	v_mov_b64_e32 v[34:35], v[2:3]
	v_mov_b64_e32 v[32:33], v[0:1]
	v_mov_b64_e32 v[28:29], v[12:13]
	v_mov_b64_e32 v[26:27], v[10:11]
	v_mov_b64_e32 v[24:25], v[8:9]
	v_mov_b64_e32 v[22:23], v[6:7]
	v_mov_b64_e32 v[20:21], v[4:5]
	v_mov_b64_e32 v[18:19], v[2:3]
	v_mov_b64_e32 v[16:17], v[0:1]
	v_readlane_b32 s85, v252, 5
	v_readlane_b32 s86, v252, 6
	s_mov_b32 s74, 0x7f800000
	s_mov_b32 s75, 0x2b000
	s_mov_b64 s[78:79], 0x800
	s_movk_i32 s77, 0x1ff
	s_waitcnt lgkmcnt(0)
	s_barrier
; #define SBAR() __builtin_amdgcn_sched_barrier(0)
; #define SLOAD(i, k0) do { sr_[i].vs0 = St::ld8(&Vh[(long)((k0) + sr) * LDK + sc]); sr_[i].vs1 = St::ld8(&Vh[(long)((k0) + 32 + sr) * LDK + sc]); \
;     sr_[i].ks0 = St::ld8(&Kh[(long)((k0) + sr) * LDK + sc]); sr_[i].ks1 = St::ld8(&Kh[(long)((k0) + 32 + sr) * LDK + sc]); } while (0)
; __device__ __forceinline__ void finishSM(f32x16& p0, f32x16& p1, float alpha, float& l_reg, bf16x8& pa0, bf16x8& pa1, bf16x8& pa2, bf16x8& pa3) {
;   for (int r = 0; r < 16; ++r) p1[r] = __builtin_amdgcn_exp2f(p1[r]);
;   float ps = 0; for (int r = 0; r < 16; ++r) ps += p0[r]; for (int r = 0; r < 16; ++r) ps += p1[r];
;   { auto rr = __builtin_amdgcn_permlane32_swap(__float_as_uint(ps), __float_as_uint(ps), false, false);
;     ps = __uint_as_float(rr[0]) + __uint_as_float(rr[1]); }
;   l_reg = l_reg * alpha + ps;
;     ...
;   PK4(p0, 0, pa0); PK4(p0, 8, pa1); PK4(p1, 0, pa2); PK4(p1, 8, pa3);
;     ...
; }
; __device__ __forceinline__ void qkt(f32x16& p0, f32x16& p1, const bf16* Ks, const bf16x8* qr, int r32, int hi) {
;   p0 = f32x16{}; p1 = f32x16{};
;   for (int d0 = 0; d0 < 8; ++d0) { int cb = (d0 * 16 + hi * 8) * 2;
;     bf16x8 b0 = *reinterpret_cast<const bf16x8*>((const char*)Ks + KSWZ(r32, cb));
;     bf16x8 b1 = *reinterpret_cast<const bf16x8*>((const char*)Ks + KSWZ(32 + r32, cb));
;     p0 = __builtin_amdgcn_mfma_f32_32x32x16_bf16(b0, qr[d0], p0, 0, 0, 0);
;     p1 = __builtin_amdgcn_mfma_f32_32x32x16_bf16(b1, qr[d0], p1, 0, 0, 0); }
; template <typename TQ>
; __device__ __forceinline__ void attn_dense_body(const TQ* __restrict__ Qb, const bf16* __restrict__ Kh, const bf16* __restrict__ Vh,
;                                                 unsigned short* __restrict__ Ob, int seq, char* lds) {
;     ...
;   for (int j = 1; j + 1 < NT; j += 2) {
;     SBAR(); qkt(pB0, pB1, (bf16*)((char*)K_lds + SHM_K), qr, r32, hi);
;     finishSM(pA0, pA1, alA, l_reg, pa0, pa1, pa2, pa3); SBAR();
;     SLOAD(SO, (j + SDEPTH) * KVBLK); SBAR();
	v_readlane_b32 s87, v252, 7
	s_waitcnt vmcnt(0)
	ds_write_b128 v189, v[132:135] offset:32768
	ds_write_b128 v190, v[140:143] offset:32768
	v_lshrrev_b32_e32 v138, 6, v211
	v_lshrrev_b32_e32 v136, 4, v246
	v_lshl_add_u32 v136, v138, 3, v136
	v_and_b32_e32 v129, 15, v246
	v_and_b32_e32 v128, 7, v136
	v_xor_b32_e32 v129, v129, v128
	v_lshlrev_b32_e32 v129, 4, v129
	v_lshl_add_u32 v128, v136, 8, v129
	v_xor_b32_e32 v129, 64, v129
	v_add_u32_e32 v136, 4, v136
	v_lshl_add_u32 v129, v136, 8, v129
	v_and_b32_e32 v136, 6, v138
	v_lshlrev_b32_e32 v136, 3, v136
	v_bfe_u32 v137, v246, 2, 2
	v_add_u32_e32 v136, v136, v137
	v_bfe_u32 v137, v246, 4, 1
	v_lshl_add_u32 v136, v137, 3, v136
	v_and_b32_e32 v137, 1, v138
	v_lshl_add_u32 v136, v137, 2, v136
	v_lshlrev_b32_e32 v136, 8, v136
	v_bfe_u32 v137, v246, 5, 1
	v_lshl_add_u32 v136, v137, 6, v136
	v_and_b32_e32 v137, 3, v246
	v_lshl_add_u32 v130, v137, 4, v136
	v_add_u32_e32 v131, 0x80, v130
	v_readfirstlane_b32 s5, v211
	s_nop 3
	s_lshr_b32 s5, s5, 6
	s_lshl_b32 s5, s5, 11
	s_add_u32 s6, s6, 0xc000
	s_addc_u32 s7, s7, 0
	s_add_u32 s68, s68, 0x8000
	s_addc_u32 s69, s69, 0
.LBB0_76:
	ds_read_b128 v[64:67], v193 offset:49152
	ds_read_b128 v[68:71], v193 offset:57344
	ds_read_b128 v[222:225], v198 offset:49152
	ds_read_b128 v[226:229], v198 offset:57344
	v_add_f32_e32 v160, 0, v161
	v_add_f32_e32 v160, v175, v160
	s_waitcnt lgkmcnt(3)
	v_mfma_f32_32x32x16_bf16 v[80:95], v[64:67], v[112:115], 0
	v_add_f32_e32 v160, v162, v160
	v_add_f32_e32 v160, v205, v160
	v_add_f32_e32 v160, v174, v160
	v_add_f32_e32 v160, v214, v160
	v_add_f32_e32 v160, v163, v160
	v_add_f32_e32 v160, v173, v160
	v_add_f32_e32 v160, v164, v160
	s_waitcnt lgkmcnt(2)
	v_mfma_f32_32x32x16_bf16 v[64:79], v[68:71], v[112:115], 0
	v_add_f32_e32 v160, v171, v160
	v_add_f32_e32 v160, v165, v160
	v_add_f32_e32 v160, v172, v160
	v_exp_f32_e32 v158, v158
	v_add_f32_e32 v160, v166, v160
	v_exp_f32_e32 v159, v159
	v_add_f32_e32 v160, v169, v160
	s_waitcnt lgkmcnt(1)
	v_mfma_f32_32x32x16_bf16 v[80:95], v[222:225], v[108:111], v[80:95]
	v_exp_f32_e32 v156, v156
	v_add_f32_e32 v160, v167, v160
	v_exp_f32_e32 v157, v157
	v_add_f32_e32 v160, v170, v160
	v_exp_f32_e32 v152, v152
	v_add_f32_e32 v160, v158, v160
	v_exp_f32_e32 v153, v153
	s_waitcnt lgkmcnt(0)
	v_mfma_f32_32x32x16_bf16 v[64:79], v[226:229], v[108:111], v[64:79]
	ds_read_b128 v[222:225], v197 offset:49152
	ds_read_b128 v[226:229], v197 offset:57344
	v_add_f32_e32 v160, v159, v160
	v_exp_f32_e32 v148, v148
	v_add_f32_e32 v160, v156, v160
	v_exp_f32_e32 v149, v149
	v_add_f32_e32 v160, v157, v160
	v_exp_f32_e32 v146, v146
	s_waitcnt lgkmcnt(1)
	v_mfma_f32_32x32x16_bf16 v[80:95], v[222:225], v[120:123], v[80:95]
	v_add_f32_e32 v160, v152, v160
	v_exp_f32_e32 v147, v147
	v_add_f32_e32 v160, v153, v160
	v_exp_f32_e32 v154, v154
	v_add_f32_e32 v160, v148, v160
	v_exp_f32_e32 v155, v155
	v_add_f32_e32 v160, v149, v160
	s_waitcnt lgkmcnt(0)
	v_mfma_f32_32x32x16_bf16 v[64:79], v[226:229], v[120:123], v[64:79]
	ds_read_b128 v[222:225], v196 offset:49152
	ds_read_b128 v[226:229], v196 offset:57344
	v_exp_f32_e32 v150, v150
	v_add_f32_e32 v160, v146, v160
	v_exp_f32_e32 v151, v151
	v_add_f32_e32 v160, v147, v160
	v_exp_f32_e32 v144, v144
	v_add_f32_e32 v160, v154, v160
	s_waitcnt lgkmcnt(1)
	v_mfma_f32_32x32x16_bf16 v[80:95], v[222:225], v[124:127], v[80:95]
	v_exp_f32_e32 v145, v145
	v_add_f32_e32 v160, v155, v160
	v_add_f32_e32 v160, v150, v160
	v_add_f32_e32 v160, v151, v160
	v_add_f32_e32 v160, v144, v160
	v_add_f32_e32 v202, v145, v160
	v_mov_b32_e32 v203, v202
	s_waitcnt lgkmcnt(0)
	v_mfma_f32_32x32x16_bf16 v[64:79], v[226:229], v[124:127], v[64:79]
	ds_read_b128 v[222:225], v194 offset:49152
	ds_read_b128 v[226:229], v194 offset:57344
	v_permlane32_swap_b32_e32 v202, v203
	s_waitcnt lgkmcnt(1)
	v_mfma_f32_32x32x16_bf16 v[80:95], v[222:225], v[116:119], v[80:95]
	s_waitcnt lgkmcnt(0)
	v_mfma_f32_32x32x16_bf16 v[64:79], v[226:229], v[116:119], v[64:79]
	ds_read_b128 v[222:225], v195 offset:49152
	ds_read_b128 v[226:229], v195 offset:57344
	s_waitcnt lgkmcnt(1)
	v_mfma_f32_32x32x16_bf16 v[80:95], v[222:225], v[104:107], v[80:95]
	s_waitcnt lgkmcnt(0)
	v_mfma_f32_32x32x16_bf16 v[64:79], v[226:229], v[104:107], v[64:79]
	ds_read_b128 v[222:225], v200 offset:49152
	ds_read_b128 v[226:229], v200 offset:57344
	s_waitcnt lgkmcnt(1)
	v_mfma_f32_32x32x16_bf16 v[80:95], v[222:225], v[100:103], v[80:95]
	s_waitcnt lgkmcnt(0)
	v_mfma_f32_32x32x16_bf16 v[64:79], v[226:229], v[100:103], v[64:79]
	ds_read_b128 v[222:225], v199 offset:49152
	ds_read_b128 v[226:229], v199 offset:57344
	v_cvt_pk_bf16_f32 v160, v161, v175
	v_cvt_pk_bf16_f32 v161, v162, v205
	v_cvt_pk_bf16_f32 v162, v174, v214
	v_cvt_pk_bf16_f32 v163, v163, v173
	v_cvt_pk_bf16_f32 v164, v164, v171
	v_cvt_pk_bf16_f32 v165, v165, v172
	s_waitcnt lgkmcnt(1)
	v_mfma_f32_32x32x16_bf16 v[80:95], v[222:225], v[96:99], v[80:95]
	v_cvt_pk_bf16_f32 v166, v166, v169
	v_cvt_pk_bf16_f32 v167, v167, v170
	v_cvt_pk_bf16_f32 v170, v158, v159
	v_cvt_pk_bf16_f32 v171, v156, v157
	v_cvt_pk_bf16_f32 v172, v152, v153
	v_cvt_pk_bf16_f32 v173, v148, v149
	v_cvt_pk_bf16_f32 v204, v146, v147
	s_waitcnt lgkmcnt(0)
	v_mfma_f32_32x32x16_bf16 v[64:79], v[226:229], v[96:99], v[64:79]
	v_cvt_pk_bf16_f32 v205, v154, v155
	v_cvt_pk_bf16_f32 v206, v150, v151
	v_permlane32_swap_b32_e32 v160, v162
	v_cvt_pk_bf16_f32 v207, v144, v145
	v_permlane32_swap_b32_e32 v204, v206
	v_permlane32_swap_b32_e32 v161, v163
	v_permlane32_swap_b32_e32 v164, v166
	v_permlane32_swap_b32_e32 v165, v167
	v_permlane32_swap_b32_e32 v170, v172
	v_permlane32_swap_b32_e32 v171, v173
	v_permlane32_swap_b32_e32 v205, v207
	ds_read_b64_tr_b16 v[222:223], v188 offset:0
	ds_read_b64_tr_b16 v[224:225], v188 offset:0x800
	ds_read_b64_tr_b16 v[226:227], v188 offset:0x1000
	ds_read_b64_tr_b16 v[228:229], v188 offset:0x1800
	ds_read_b64_tr_b16 v[230:231], v188 offset:0x2000
	ds_read_b64_tr_b16 v[232:233], v188 offset:0x2800
	ds_read_b64_tr_b16 v[234:235], v188 offset:0x3000
	ds_read_b64_tr_b16 v[236:237], v188 offset:0x3800
	s_waitcnt lgkmcnt(0)
; #define SBAR() __builtin_amdgcn_sched_barrier(0)
; #define SWAIT() do { if constexpr (SDEPTH == 2) asm volatile("s_waitcnt vmcnt(4)" ::: "memory"); else asm volatile("s_waitcnt vmcnt(0)" ::: "memory"); } while (0)
; #define RESC(a) do { if (__any((a) < 1.f)) { if (hi == 0) al_l[r32] = (a); asm volatile("s_waitcnt lgkmcnt(0)" ::: "memory"); \
;     for (int d = 0; d < 4; ++d) for (int r = 0; r < 16; ++r) o[d][r] *= al_l[crow(r, hi)]; } } while (0)
; template <int D0> __device__ __forceinline__ void pv_one(f32x16& od, int vb, bf16x8 pa0, bf16x8 pa1, bf16x8 pa2, bf16x8 pa3) {
;   const s16x4 l0 = tr_read<v_rd_off(D0, 0, 0)>(vb), h0 = tr_read<v_rd_off(D0, 0, 1)>(vb), l1 = tr_read<v_rd_off(D0, 1, 0)>(vb), h1 = tr_read<v_rd_off(D0, 1, 1)>(vb);
;   const s16x4 l2 = tr_read<v_rd_off(D0, 2, 0)>(vb), h2 = tr_read<v_rd_off(D0, 2, 1)>(vb), l3 = tr_read<v_rd_off(D0, 3, 0)>(vb), h3 = tr_read<v_rd_off(D0, 3, 1)>(vb);
;   asm volatile("s_waitcnt lgkmcnt(0)" ::: "memory"); SBAR();
;     ...
;   od = __builtin_amdgcn_mfma_f32_32x32x16_bf16(pa0, PK(l0, h0), od, 0, 0, 0);
;   od = __builtin_amdgcn_mfma_f32_32x32x16_bf16(pa1, PK(l1, h1), od, 0, 0, 0);
;   od = __builtin_amdgcn_mfma_f32_32x32x16_bf16(pa2, PK(l2, h2), od, 0, 0, 0);
;   od = __builtin_amdgcn_mfma_f32_32x32x16_bf16(pa3, PK(l3, h3), od, 0, 0, 0);
;     ...
; }
; __device__ __forceinline__ void pv_d0(f32x16* o, int vb, bf16x8 pa0, bf16x8 pa1, bf16x8 pa2, bf16x8 pa3) {
;   pv_one<0>(o[0], vb, pa0, pa1, pa2, pa3); pv_one<1>(o[1], vb, pa0, pa1, pa2, pa3); pv_one<2>(o[2], vb, pa0, pa1, pa2, pa3); pv_one<3>(o[3], vb, pa0, pa1, pa2, pa3);
; template <typename TQ>
; __device__ __forceinline__ void attn_dense_body(const TQ* __restrict__ Qb, const bf16* __restrict__ Kh, const bf16* __restrict__ Vh,
;                                                 unsigned short* __restrict__ Ob, int seq, char* lds) {
;     ...
;     pv_d0(o, vb0, pa0, pa1, pa2, pa3); partialSM(pB0, pB1, m_reg, mnB, alB);
;     __syncthreads(); SWAIT(); SWRITE(0, SE);
;     RESC(alB); __syncthreads();
	s_nop 0
	v_mfma_f32_32x32x16_bf16 v[0:15], v[160:163], v[222:225], v[0:15]
	ds_read_b64_tr_b16 v[222:223], v188 offset:0x200
	ds_read_b64_tr_b16 v[224:225], v188 offset:0xa00
	v_mfma_f32_32x32x16_bf16 v[0:15], v[164:167], v[226:229], v[0:15]
	ds_read_b64_tr_b16 v[226:227], v188 offset:0x1200
	ds_read_b64_tr_b16 v[228:229], v188 offset:0x1a00
	v_mfma_f32_32x32x16_bf16 v[0:15], v[170:173], v[230:233], v[0:15]
	ds_read_b64_tr_b16 v[230:231], v188 offset:0x2200
	ds_read_b64_tr_b16 v[232:233], v188 offset:0x2a00
	v_mfma_f32_32x32x16_bf16 v[0:15], v[204:207], v[234:237], v[0:15]
	ds_read_b64_tr_b16 v[234:235], v188 offset:0x3200
	ds_read_b64_tr_b16 v[236:237], v188 offset:0x3a00
	s_waitcnt lgkmcnt(0)
	v_mfma_f32_32x32x16_bf16 v[48:63], v[160:163], v[222:225], v[48:63]
	ds_read_b64_tr_b16 v[222:223], v188 offset:0x400
	ds_read_b64_tr_b16 v[224:225], v188 offset:0xc00
	v_mfma_f32_32x32x16_bf16 v[48:63], v[164:167], v[226:229], v[48:63]
	ds_read_b64_tr_b16 v[226:227], v188 offset:0x1400
	ds_read_b64_tr_b16 v[228:229], v188 offset:0x1c00
	v_mfma_f32_32x32x16_bf16 v[48:63], v[170:173], v[230:233], v[48:63]
	ds_read_b64_tr_b16 v[230:231], v188 offset:0x2400
	ds_read_b64_tr_b16 v[232:233], v188 offset:0x2c00
	v_mfma_f32_32x32x16_bf16 v[48:63], v[204:207], v[234:237], v[48:63]
	ds_read_b64_tr_b16 v[234:235], v188 offset:0x3400
	ds_read_b64_tr_b16 v[236:237], v188 offset:0x3c00
	s_waitcnt lgkmcnt(0)
	v_mfma_f32_32x32x16_bf16 v[32:47], v[160:163], v[222:225], v[32:47]
	ds_read_b64_tr_b16 v[222:223], v188 offset:0x600
	ds_read_b64_tr_b16 v[224:225], v188 offset:0xe00
	v_mfma_f32_32x32x16_bf16 v[32:47], v[164:167], v[226:229], v[32:47]
	ds_read_b64_tr_b16 v[226:227], v188 offset:0x1600
	ds_read_b64_tr_b16 v[228:229], v188 offset:0x1e00
	v_mfma_f32_32x32x16_bf16 v[32:47], v[170:173], v[230:233], v[32:47]
	ds_read_b64_tr_b16 v[230:231], v188 offset:0x2600
	ds_read_b64_tr_b16 v[232:233], v188 offset:0x2e00
	v_mfma_f32_32x32x16_bf16 v[32:47], v[204:207], v[234:237], v[32:47]
	ds_read_b64_tr_b16 v[234:235], v188 offset:0x3600
	ds_read_b64_tr_b16 v[236:237], v188 offset:0x3e00
	s_waitcnt lgkmcnt(0)
	v_mfma_f32_32x32x16_bf16 v[16:31], v[160:163], v[222:225], v[16:31]
	v_max_f32_e32 v160, v81, v81
	v_max_f32_e32 v161, v80, v80
	v_max_f32_e32 v160, v161, v160
	v_max3_f32 v160, v160, v82, v83
	v_max3_f32 v160, v160, v84, v85
	v_max3_f32 v160, v160, v86, v87
	v_max3_f32 v160, v160, v88, v89
	v_max3_f32 v160, v160, v90, v91
	v_max3_f32 v160, v160, v92, v93
	v_mfma_f32_32x32x16_bf16 v[16:31], v[164:167], v[226:229], v[16:31]
	v_max3_f32 v160, v160, v94, v95
	v_max3_f32 v160, v160, v64, v65
	v_max3_f32 v160, v160, v66, v67
	v_max3_f32 v160, v160, v68, v69
	v_max3_f32 v160, v160, v70, v71
	v_max3_f32 v160, v160, v72, v73
	v_max3_f32 v160, v160, v74, v75
	v_max3_f32 v160, v160, v76, v77
	v_mfma_f32_32x32x16_bf16 v[16:31], v[170:173], v[230:233], v[16:31]
	v_max3_f32 v160, v160, v78, v79
	v_mov_b32_e32 v161, v160
	s_nop 1
	v_permlane32_swap_b32_e32 v160, v161
	v_max_f32_e32 v161, v161, v161
	v_max_f32_e32 v160, v160, v160
	v_max_f32_e32 v160, v160, v161
	v_sub_f32_e32 v161, v160, v168
	v_cmp_ge_f32_e32 vcc, s4, v161
	v_max_f32_e32 v161, v168, v168
	v_max_f32_e32 v160, v161, v160
	v_mfma_f32_32x32x16_bf16 v[16:31], v[204:207], v[234:237], v[16:31]
	v_sub_f32_e32 v161, v168, v160
	v_mul_f32_e32 v161, 0x3e0293ee, v161
	v_exp_f32_e32 v161, v161
	s_cmp_eq_u64 vcc, exec
	s_cselect_b64 s[0:1], -1, 0
	s_barrier
	v_cndmask_b32_e64 v204, v161, 1.0, s[0:1]
	v_cmp_gt_f32_e32 vcc, 1.0, v204
	s_add_i32 m0, s5, 0xc000
	s_nop 0
	global_load_lds_dwordx4 v128, s[6:7]
	s_add_i32 m0, s5, 0xc400
	s_nop 0
	global_load_lds_dwordx4 v129, s[6:7]
	s_add_i32 m0, s5, 0x0
	s_nop 0
	global_load_lds_dwordx4 v130, s[68:69]
	s_add_i32 m0, s5, 0x400
	s_nop 0
	global_load_lds_dwordx4 v131, s[68:69]
	s_add_u32 s6, s6, 0x4000
	s_addc_u32 s7, s7, 0
	s_add_u32 s68, s68, 0x4000
	s_addc_u32 s69, s69, 0
	s_cbranch_vccz .LBB0_80
	s_and_saveexec_b64 s[42:43], s[38:39]
	ds_write_b32 v185, v204 offset:128
	s_or_b64 exec, exec, s[42:43]
	s_waitcnt lgkmcnt(0)
	v_add_u32_e32 v161, v184, v208
	ds_read_b128 v[162:165], v161 offset:224
	ds_read_b128 v[170:173], v161 offset:192
	ds_read_b128 v[222:225], v161 offset:160
	ds_read_b128 v[226:229], v161 offset:128
	s_waitcnt lgkmcnt(3)
	v_pk_mul_f32 v[12:13], v[12:13], v[162:163]
	s_waitcnt lgkmcnt(2)
	v_pk_mul_f32 v[8:9], v[8:9], v[170:171]
	s_waitcnt lgkmcnt(1)
	v_pk_mul_f32 v[4:5], v[4:5], v[222:223]
	v_pk_mul_f32 v[14:15], v[14:15], v[164:165]
	v_pk_mul_f32 v[10:11], v[10:11], v[172:173]
	v_pk_mul_f32 v[6:7], v[6:7], v[224:225]
	s_waitcnt lgkmcnt(0)
	v_pk_mul_f32 v[2:3], v[2:3], v[228:229]
	v_pk_mul_f32 v[0:1], v[0:1], v[226:227]
	v_pk_mul_f32 v[60:61], v[60:61], v[162:163]
	v_pk_mul_f32 v[56:57], v[56:57], v[170:171]
	v_pk_mul_f32 v[52:53], v[52:53], v[222:223]
	v_pk_mul_f32 v[62:63], v[62:63], v[164:165]
	v_pk_mul_f32 v[58:59], v[58:59], v[172:173]
	v_pk_mul_f32 v[54:55], v[54:55], v[224:225]
	v_pk_mul_f32 v[50:51], v[50:51], v[228:229]
	v_pk_mul_f32 v[48:49], v[48:49], v[226:227]
	v_pk_mul_f32 v[44:45], v[44:45], v[162:163]
	v_pk_mul_f32 v[40:41], v[40:41], v[170:171]
	v_pk_mul_f32 v[36:37], v[36:37], v[222:223]
	v_pk_mul_f32 v[46:47], v[46:47], v[164:165]
	v_pk_mul_f32 v[42:43], v[42:43], v[172:173]
	v_pk_mul_f32 v[38:39], v[38:39], v[224:225]
	v_pk_mul_f32 v[34:35], v[34:35], v[228:229]
	v_pk_mul_f32 v[32:33], v[32:33], v[226:227]
	v_pk_mul_f32 v[28:29], v[28:29], v[162:163]
	v_pk_mul_f32 v[24:25], v[24:25], v[170:171]
	v_pk_mul_f32 v[20:21], v[20:21], v[222:223]
	v_pk_mul_f32 v[30:31], v[30:31], v[164:165]
	v_pk_mul_f32 v[26:27], v[26:27], v[172:173]
	v_pk_mul_f32 v[22:23], v[22:23], v[224:225]
	v_pk_mul_f32 v[18:19], v[18:19], v[228:229]
	v_pk_mul_f32 v[16:17], v[16:17], v[226:227]
; __device__ __forceinline__ void partialSM(f32x16& p0, f32x16& p1, float& m_reg, float& mn, float& alpha) {
;   constexpr float C = SCALE * 1.4426950408889634f;
;   float pmax = p0[0]; for (int r = 1; r < 16; ++r) pmax = fmaxf(pmax, p0[r]); for (int r = 0; r < 16; ++r) pmax = fmaxf(pmax, p1[r]);
;   { auto rr = __builtin_amdgcn_permlane32_swap(__float_as_uint(pmax), __float_as_uint(pmax), false, false);
;     pmax = fmaxf(__uint_as_float(rr[0]), __uint_as_float(rr[1])); }
;   if (__builtin_expect(__all(pmax - m_reg <= THR / SCALE), 1)) { mn = m_reg; alpha = 1.f; }
;   else { mn = fmaxf(m_reg, pmax); alpha = __builtin_amdgcn_exp2f((m_reg - mn) * C); m_reg = mn; }
;   float mnC = -mn * C;
;   for (int r = 0; r < 16; ++r) p0[r] = fmaf(p0[r], C, mnC); for (int r = 0; r < 16; ++r) p1[r] = fmaf(p1[r], C, mnC);
;   for (int r = 0; r < 16; ++r) p0[r] = __builtin_amdgcn_exp2f(p0[r]);
; }
; __device__ __forceinline__ void finishSM(f32x16& p0, f32x16& p1, float alpha, float& l_reg, bf16x8& pa0, bf16x8& pa1, bf16x8& pa2, bf16x8& pa3) {
;   for (int r = 0; r < 16; ++r) p1[r] = __builtin_amdgcn_exp2f(p1[r]);
;   float ps = 0; for (int r = 0; r < 16; ++r) ps += p0[r]; for (int r = 0; r < 16; ++r) ps += p1[r];
;   { auto rr = __builtin_amdgcn_permlane32_swap(__float_as_uint(ps), __float_as_uint(ps), false, false);
;     ps = __uint_as_float(rr[0]) + __uint_as_float(rr[1]); }
;   l_reg = l_reg * alpha + ps;
;     ...
;   PK4(p0, 0, pa0); PK4(p0, 8, pa1); PK4(p1, 0, pa2); PK4(p1, 8, pa3);
;     ...
; }
; __device__ __forceinline__ void qkt(f32x16& p0, f32x16& p1, const bf16* Ks, const bf16x8* qr, int r32, int hi) {
;   p0 = f32x16{}; p1 = f32x16{};
;   for (int d0 = 0; d0 < 8; ++d0) { int cb = (d0 * 16 + hi * 8) * 2;
;     bf16x8 b0 = *reinterpret_cast<const bf16x8*>((const char*)Ks + KSWZ(r32, cb));
;     bf16x8 b1 = *reinterpret_cast<const bf16x8*>((const char*)Ks + KSWZ(32 + r32, cb));
; template <typename TQ>
; __device__ __forceinline__ void attn_dense_body(const TQ* __restrict__ Qb, const bf16* __restrict__ Kh, const bf16* __restrict__ Vh,
;                                                 unsigned short* __restrict__ Ob, int seq, char* lds) {
;     ...
;     RESC(alB); __syncthreads();
;     SBAR(); qkt(pA0, pA1, K_lds, qr, r32, hi);
;     finishSM(pB0, pB1, alB, l_reg, pa0, pa1, pa2, pa3); SBAR();
;     if (SDEPTH == 1 || j + 3 < NT) SLOAD(SE, (j + 1 + SDEPTH) * KVBLK); SBAR();
.LBB0_80:
	v_cndmask_b32_e64 v205, v160, v168, s[0:1]
	v_mul_f32_e32 v206, 0xbe0293ee, v205
	v_fmamk_f32 v80, v80, 0x3e0293ee, v206
	v_fmamk_f32 v81, v81, 0x3e0293ee, v206
	v_fmamk_f32 v82, v82, 0x3e0293ee, v206
	v_fmamk_f32 v83, v83, 0x3e0293ee, v206
	v_fmamk_f32 v84, v84, 0x3e0293ee, v206
	v_fmamk_f32 v85, v85, 0x3e0293ee, v206
	v_fmamk_f32 v86, v86, 0x3e0293ee, v206
	v_fmamk_f32 v87, v87, 0x3e0293ee, v206
	v_fmamk_f32 v88, v88, 0x3e0293ee, v206
	v_fmamk_f32 v89, v89, 0x3e0293ee, v206
	v_fmamk_f32 v90, v90, 0x3e0293ee, v206
	v_fmamk_f32 v91, v91, 0x3e0293ee, v206
	v_fmamk_f32 v92, v92, 0x3e0293ee, v206
	v_fmamk_f32 v93, v93, 0x3e0293ee, v206
	v_fmamk_f32 v94, v94, 0x3e0293ee, v206
	v_fmamk_f32 v95, v95, 0x3e0293ee, v206
	v_exp_f32_e32 v160, v80
	v_exp_f32_e32 v175, v81
	v_exp_f32_e32 v161, v82
	v_exp_f32_e32 v174, v83
	v_exp_f32_e32 v162, v84
	v_exp_f32_e32 v173, v85
	v_exp_f32_e32 v163, v86
	v_exp_f32_e32 v172, v87
	v_exp_f32_e32 v164, v88
	v_exp_f32_e32 v171, v89
	v_exp_f32_e32 v165, v90
	v_exp_f32_e32 v170, v91
	v_exp_f32_e32 v166, v92
	v_exp_f32_e32 v169, v93
	v_exp_f32_e32 v167, v94
	v_exp_f32_e32 v168, v95
	v_fmamk_f32 v227, v64, 0x3e0293ee, v206
	v_fmamk_f32 v228, v65, 0x3e0293ee, v206
	v_fmamk_f32 v229, v66, 0x3e0293ee, v206
	v_fmamk_f32 v230, v67, 0x3e0293ee, v206
	v_fmamk_f32 v231, v68, 0x3e0293ee, v206
	v_fmamk_f32 v214, v69, 0x3e0293ee, v206
	v_fmamk_f32 v215, v70, 0x3e0293ee, v206
	v_fmamk_f32 v222, v71, 0x3e0293ee, v206
	v_fmamk_f32 v223, v72, 0x3e0293ee, v206
	v_fmamk_f32 v224, v73, 0x3e0293ee, v206
	v_fmamk_f32 v225, v74, 0x3e0293ee, v206
	v_fmamk_f32 v226, v75, 0x3e0293ee, v206
	v_fmamk_f32 v207, v76, 0x3e0293ee, v206
	v_fmamk_f32 v232, v77, 0x3e0293ee, v206
	v_fmamk_f32 v233, v78, 0x3e0293ee, v206
	v_fmac_f32_e32 v206, 0x3e0293ee, v79
	s_waitcnt lgkmcnt(0)
	s_waitcnt vmcnt(4)
	s_barrier
	ds_read_b128 v[64:67], v193 offset:32768
	ds_read_b128 v[68:71], v193 offset:40960
	ds_read_b128 v[234:237], v198 offset:32768
	ds_read_b128 v[238:241], v198 offset:40960
	v_exp_f32_e32 v216, v227
	v_exp_f32_e32 v227, v229
	s_waitcnt lgkmcnt(3)
	v_mfma_f32_32x32x16_bf16 v[80:95], v[64:67], v[112:115], 0
	v_exp_f32_e32 v229, v231
	v_exp_f32_e32 v231, v232
	v_exp_f32_e32 v232, v233
	v_exp_f32_e32 v233, v206
	v_add_f32_e32 v206, 0, v160
	v_add_f32_e32 v206, v175, v206
	v_add_f32_e32 v206, v161, v206
	s_waitcnt lgkmcnt(2)
	v_mfma_f32_32x32x16_bf16 v[64:79], v[68:71], v[112:115], 0
	v_add_f32_e32 v206, v174, v206
	v_add_f32_e32 v206, v162, v206
	v_add_f32_e32 v206, v173, v206
	v_add_f32_e32 v206, v163, v206
	v_add_f32_e32 v206, v172, v206
	v_add_f32_e32 v206, v164, v206
	v_add_f32_e32 v206, v171, v206
	s_waitcnt lgkmcnt(1)
	v_mfma_f32_32x32x16_bf16 v[80:95], v[234:237], v[108:111], v[80:95]
	v_add_f32_e32 v206, v165, v206
	v_add_f32_e32 v206, v170, v206
	v_add_f32_e32 v206, v166, v206
	v_exp_f32_e32 v217, v228
	v_add_f32_e32 v206, v169, v206
	v_add_f32_e32 v206, v167, v206
	v_exp_f32_e32 v228, v230
	s_waitcnt lgkmcnt(0)
	v_mfma_f32_32x32x16_bf16 v[64:79], v[238:241], v[108:111], v[64:79]
	ds_read_b128 v[234:237], v197 offset:32768
	ds_read_b128 v[238:241], v197 offset:40960
	v_add_f32_e32 v206, v168, v206
	v_add_f32_e32 v206, v216, v206
	v_exp_f32_e32 v214, v214
	v_add_f32_e32 v206, v217, v206
	v_exp_f32_e32 v215, v215
	v_add_f32_e32 v206, v227, v206
	s_waitcnt lgkmcnt(1)
	v_mfma_f32_32x32x16_bf16 v[80:95], v[234:237], v[120:123], v[80:95]
	v_exp_f32_e32 v222, v222
	v_add_f32_e32 v206, v228, v206
	v_exp_f32_e32 v223, v223
	v_add_f32_e32 v206, v229, v206
	v_exp_f32_e32 v224, v224
	v_add_f32_e32 v206, v214, v206
	v_exp_f32_e32 v225, v225
	s_waitcnt lgkmcnt(0)
	v_mfma_f32_32x32x16_bf16 v[64:79], v[238:241], v[120:123], v[64:79]
	ds_read_b128 v[234:237], v196 offset:32768
	ds_read_b128 v[238:241], v196 offset:40960
	v_add_f32_e32 v206, v215, v206
	v_exp_f32_e32 v226, v226
	v_add_f32_e32 v206, v222, v206
	v_exp_f32_e32 v230, v207
	v_add_f32_e32 v206, v223, v206
	v_add_f32_e32 v206, v224, v206
	s_waitcnt lgkmcnt(1)
	v_mfma_f32_32x32x16_bf16 v[80:95], v[234:237], v[124:127], v[80:95]
	v_add_f32_e32 v206, v225, v206
	v_add_f32_e32 v206, v226, v206
	v_add_f32_e32 v206, v230, v206
	v_add_f32_e32 v206, v231, v206
	v_add_f32_e32 v206, v232, v206
	v_add_f32_e32 v206, v233, v206
	v_mov_b32_e32 v207, v206
	s_waitcnt lgkmcnt(0)
	v_mfma_f32_32x32x16_bf16 v[64:79], v[238:241], v[124:127], v[64:79]
	ds_read_b128 v[234:237], v194 offset:32768
	ds_read_b128 v[238:241], v194 offset:40960
	v_permlane32_swap_b32_e32 v206, v207
	s_waitcnt lgkmcnt(1)
	v_mfma_f32_32x32x16_bf16 v[80:95], v[234:237], v[116:119], v[80:95]
	s_waitcnt lgkmcnt(0)
	v_mfma_f32_32x32x16_bf16 v[64:79], v[238:241], v[116:119], v[64:79]
	ds_read_b128 v[234:237], v195 offset:32768
	ds_read_b128 v[238:241], v195 offset:40960
	s_waitcnt lgkmcnt(1)
	v_mfma_f32_32x32x16_bf16 v[80:95], v[234:237], v[104:107], v[80:95]
	s_waitcnt lgkmcnt(0)
	v_mfma_f32_32x32x16_bf16 v[64:79], v[238:241], v[104:107], v[64:79]
	ds_read_b128 v[234:237], v200 offset:32768
	ds_read_b128 v[238:241], v200 offset:40960
	s_waitcnt lgkmcnt(1)
	v_mfma_f32_32x32x16_bf16 v[80:95], v[234:237], v[100:103], v[80:95]
	s_waitcnt lgkmcnt(0)
	v_mfma_f32_32x32x16_bf16 v[64:79], v[238:241], v[100:103], v[64:79]
	ds_read_b128 v[234:237], v199 offset:32768
	ds_read_b128 v[238:241], v199 offset:40960
	v_cvt_pk_bf16_f32 v160, v160, v175
	v_cvt_pk_bf16_f32 v161, v161, v174
	v_cvt_pk_bf16_f32 v162, v162, v173
	v_cvt_pk_bf16_f32 v163, v163, v172
	v_cvt_pk_bf16_f32 v164, v164, v171
	v_cvt_pk_bf16_f32 v165, v165, v170
	s_waitcnt lgkmcnt(1)
	v_mfma_f32_32x32x16_bf16 v[80:95], v[234:237], v[96:99], v[80:95]
	v_cvt_pk_bf16_f32 v166, v166, v169
	v_cvt_pk_bf16_f32 v167, v167, v168
	v_cvt_pk_bf16_f32 v168, v216, v217
	v_cvt_pk_bf16_f32 v169, v227, v228
	v_cvt_pk_bf16_f32 v170, v229, v214
	v_cvt_pk_bf16_f32 v171, v215, v222
	v_cvt_pk_bf16_f32 v172, v223, v224
	s_waitcnt lgkmcnt(0)
	v_mfma_f32_32x32x16_bf16 v[64:79], v[238:241], v[96:99], v[64:79]
	v_cvt_pk_bf16_f32 v173, v225, v226
	v_cvt_pk_bf16_f32 v174, v230, v231
	v_cvt_pk_bf16_f32 v175, v232, v233
	v_permlane32_swap_b32_e32 v160, v162
	v_permlane32_swap_b32_e32 v161, v163
	v_permlane32_swap_b32_e32 v164, v166
	v_permlane32_swap_b32_e32 v165, v167
	v_permlane32_swap_b32_e32 v168, v170
	v_permlane32_swap_b32_e32 v169, v171
	v_permlane32_swap_b32_e32 v172, v174
	v_permlane32_swap_b32_e32 v173, v175
	s_cmp_ge_u32 s2, s27
	s_cselect_b64 s[42:43], -1, 0
	s_and_b64 vcc, exec, s[42:43]
	s_cbranch_vccnz .LBB0_82
; #define SBAR() __builtin_amdgcn_sched_barrier(0)
; #define SLOAD(i, k0) do { sr_[i].vs0 = St::ld8(&Vh[(long)((k0) + sr) * LDK + sc]); sr_[i].vs1 = St::ld8(&Vh[(long)((k0) + 32 + sr) * LDK + sc]); \
;     sr_[i].ks0 = St::ld8(&Kh[(long)((k0) + sr) * LDK + sc]); sr_[i].ks1 = St::ld8(&Kh[(long)((k0) + 32 + sr) * LDK + sc]); } while (0)
; #define SWAIT() do { if constexpr (SDEPTH == 2) asm volatile("s_waitcnt vmcnt(4)" ::: "memory"); else asm volatile("s_waitcnt vmcnt(0)" ::: "memory"); } while (0)
; #define RESC(a) do { if (__any((a) < 1.f)) { if (hi == 0) al_l[r32] = (a); asm volatile("s_waitcnt lgkmcnt(0)" ::: "memory"); \
;     for (int d = 0; d < 4; ++d) for (int r = 0; r < 16; ++r) o[d][r] *= al_l[crow(r, hi)]; } } while (0)
; template <int D0> __device__ __forceinline__ void pv_one(f32x16& od, int vb, bf16x8 pa0, bf16x8 pa1, bf16x8 pa2, bf16x8 pa3) {
;   const s16x4 l0 = tr_read<v_rd_off(D0, 0, 0)>(vb), h0 = tr_read<v_rd_off(D0, 0, 1)>(vb), l1 = tr_read<v_rd_off(D0, 1, 0)>(vb), h1 = tr_read<v_rd_off(D0, 1, 1)>(vb);
;   const s16x4 l2 = tr_read<v_rd_off(D0, 2, 0)>(vb), h2 = tr_read<v_rd_off(D0, 2, 1)>(vb), l3 = tr_read<v_rd_off(D0, 3, 0)>(vb), h3 = tr_read<v_rd_off(D0, 3, 1)>(vb);
;   asm volatile("s_waitcnt lgkmcnt(0)" ::: "memory"); SBAR();
;     ...
;   od = __builtin_amdgcn_mfma_f32_32x32x16_bf16(pa0, PK(l0, h0), od, 0, 0, 0);
;   od = __builtin_amdgcn_mfma_f32_32x32x16_bf16(pa1, PK(l1, h1), od, 0, 0, 0);
;   od = __builtin_amdgcn_mfma_f32_32x32x16_bf16(pa2, PK(l2, h2), od, 0, 0, 0);
;   od = __builtin_amdgcn_mfma_f32_32x32x16_bf16(pa3, PK(l3, h3), od, 0, 0, 0);
;     ...
; }
; __device__ __forceinline__ void pv_d0(f32x16* o, int vb, bf16x8 pa0, bf16x8 pa1, bf16x8 pa2, bf16x8 pa3) {
;   pv_one<0>(o[0], vb, pa0, pa1, pa2, pa3); pv_one<1>(o[1], vb, pa0, pa1, pa2, pa3); pv_one<2>(o[2], vb, pa0, pa1, pa2, pa3); pv_one<3>(o[3], vb, pa0, pa1, pa2, pa3);
; template <typename TQ>
; __device__ __forceinline__ void attn_dense_body(const TQ* __restrict__ Qb, const bf16* __restrict__ Kh, const bf16* __restrict__ Vh,
;                                                 unsigned short* __restrict__ Ob, int seq, char* lds) {
;     ...
;     if (SDEPTH == 1 || j + 3 < NT) SLOAD(SE, (j + 1 + SDEPTH) * KVBLK); SBAR();
;     pv_d0(o, vb0 + (int)SHM_V, pa0, pa1, pa2, pa3); partialSM(pA0, pA1, m_reg, mnA, alA);
;     __syncthreads(); SWAIT(); SWRITE(1, SO);
;     RESC(alA); __syncthreads();
.LBB0_82:
	ds_read_b64_tr_b16 v[222:223], v187 offset:0
	ds_read_b64_tr_b16 v[224:225], v187 offset:0x800
	ds_read_b64_tr_b16 v[226:227], v187 offset:0x1000
	ds_read_b64_tr_b16 v[228:229], v187 offset:0x1800
	ds_read_b64_tr_b16 v[230:231], v187 offset:0x2000
	ds_read_b64_tr_b16 v[232:233], v187 offset:0x2800
	ds_read_b64_tr_b16 v[234:235], v187 offset:0x3000
	ds_read_b64_tr_b16 v[236:237], v187 offset:0x3800
	s_waitcnt lgkmcnt(0)
	s_nop 0
	v_mfma_f32_32x32x16_bf16 v[0:15], v[160:163], v[222:225], v[0:15]
	ds_read_b64_tr_b16 v[222:223], v187 offset:0x200
	ds_read_b64_tr_b16 v[224:225], v187 offset:0xa00
	v_mfma_f32_32x32x16_bf16 v[0:15], v[164:167], v[226:229], v[0:15]
	ds_read_b64_tr_b16 v[226:227], v187 offset:0x1200
	ds_read_b64_tr_b16 v[228:229], v187 offset:0x1a00
	v_mfma_f32_32x32x16_bf16 v[0:15], v[168:171], v[230:233], v[0:15]
	ds_read_b64_tr_b16 v[230:231], v187 offset:0x2200
	ds_read_b64_tr_b16 v[232:233], v187 offset:0x2a00
	v_mfma_f32_32x32x16_bf16 v[0:15], v[172:175], v[234:237], v[0:15]
	ds_read_b64_tr_b16 v[234:235], v187 offset:0x3200
	ds_read_b64_tr_b16 v[236:237], v187 offset:0x3a00
	s_waitcnt lgkmcnt(0)
	v_mfma_f32_32x32x16_bf16 v[48:63], v[160:163], v[222:225], v[48:63]
	ds_read_b64_tr_b16 v[222:223], v187 offset:0x400
	ds_read_b64_tr_b16 v[224:225], v187 offset:0xc00
	v_mfma_f32_32x32x16_bf16 v[48:63], v[164:167], v[226:229], v[48:63]
	ds_read_b64_tr_b16 v[226:227], v187 offset:0x1400
	ds_read_b64_tr_b16 v[228:229], v187 offset:0x1c00
	v_mfma_f32_32x32x16_bf16 v[48:63], v[168:171], v[230:233], v[48:63]
	ds_read_b64_tr_b16 v[230:231], v187 offset:0x2400
	ds_read_b64_tr_b16 v[232:233], v187 offset:0x2c00
	v_mfma_f32_32x32x16_bf16 v[48:63], v[172:175], v[234:237], v[48:63]
	ds_read_b64_tr_b16 v[234:235], v187 offset:0x3400
	ds_read_b64_tr_b16 v[236:237], v187 offset:0x3c00
	s_waitcnt lgkmcnt(0)
	v_mfma_f32_32x32x16_bf16 v[32:47], v[160:163], v[222:225], v[32:47]
	ds_read_b64_tr_b16 v[222:223], v187 offset:0x600
	ds_read_b64_tr_b16 v[224:225], v187 offset:0xe00
	v_mfma_f32_32x32x16_bf16 v[32:47], v[164:167], v[226:229], v[32:47]
	ds_read_b64_tr_b16 v[226:227], v187 offset:0x1600
	ds_read_b64_tr_b16 v[228:229], v187 offset:0x1e00
	v_mfma_f32_32x32x16_bf16 v[32:47], v[168:171], v[230:233], v[32:47]
	ds_read_b64_tr_b16 v[230:231], v187 offset:0x2600
	ds_read_b64_tr_b16 v[232:233], v187 offset:0x2e00
	v_mfma_f32_32x32x16_bf16 v[32:47], v[172:175], v[234:237], v[32:47]
	ds_read_b64_tr_b16 v[234:235], v187 offset:0x3600
	ds_read_b64_tr_b16 v[236:237], v187 offset:0x3e00
	s_waitcnt lgkmcnt(0)
	v_mfma_f32_32x32x16_bf16 v[16:31], v[160:163], v[222:225], v[16:31]
	v_max_f32_e32 v160, v81, v81
	v_max_f32_e32 v161, v80, v80
	v_max_f32_e32 v160, v161, v160
	v_max3_f32 v160, v160, v82, v83
	v_max3_f32 v160, v160, v84, v85
	v_max3_f32 v160, v160, v86, v87
	v_max3_f32 v160, v160, v88, v89
	v_max3_f32 v160, v160, v90, v91
	v_max3_f32 v160, v160, v92, v93
	v_mfma_f32_32x32x16_bf16 v[16:31], v[164:167], v[226:229], v[16:31]
	v_max3_f32 v160, v160, v94, v95
	v_max3_f32 v160, v160, v64, v65
	v_max3_f32 v160, v160, v66, v67
	v_max3_f32 v160, v160, v68, v69
	v_max3_f32 v160, v160, v70, v71
	v_max3_f32 v160, v160, v72, v73
	v_max3_f32 v160, v160, v74, v75
	v_max3_f32 v160, v160, v76, v77
	v_mfma_f32_32x32x16_bf16 v[16:31], v[168:171], v[230:233], v[16:31]
	v_max3_f32 v160, v160, v78, v79
	v_mov_b32_e32 v161, v160
	s_nop 1
	v_permlane32_swap_b32_e32 v160, v161
	v_max_f32_e32 v161, v161, v161
	v_max_f32_e32 v160, v160, v160
	v_max_f32_e32 v160, v160, v161
	v_sub_f32_e32 v161, v160, v205
	v_cmp_ge_f32_e32 vcc, s4, v161
	v_max_f32_e32 v161, v205, v205
	v_max_f32_e32 v161, v161, v160
	v_mfma_f32_32x32x16_bf16 v[16:31], v[172:175], v[234:237], v[16:31]
	v_sub_f32_e32 v160, v205, v161
	v_mul_f32_e32 v160, 0x3e0293ee, v160
	v_exp_f32_e32 v160, v160
	s_cmp_eq_u64 vcc, exec
	s_cselect_b64 s[0:1], -1, 0
	s_barrier
	v_cndmask_b32_e64 v160, v160, 1.0, s[0:1]
	v_cmp_gt_f32_e32 vcc, 1.0, v160
	s_add_i32 m0, s5, 0x8000
	s_nop 0
	global_load_lds_dwordx4 v128, s[6:7]
	s_add_i32 m0, s5, 0x8400
	s_nop 0
	global_load_lds_dwordx4 v129, s[6:7]
	s_add_i32 m0, s5, 0x4000
	s_nop 0
	global_load_lds_dwordx4 v130, s[68:69]
	s_add_i32 m0, s5, 0x4400
	s_nop 0
	global_load_lds_dwordx4 v131, s[68:69]
	s_add_u32 s6, s6, 0x4000
	s_addc_u32 s7, s7, 0
	s_add_u32 s68, s68, 0x4000
	s_addc_u32 s69, s69, 0
	s_cbranch_vccz .LBB0_86
	s_and_saveexec_b64 s[46:47], s[38:39]
	ds_write_b32 v185, v160 offset:128
	s_or_b64 exec, exec, s[46:47]
	s_waitcnt lgkmcnt(0)
	v_add_u32_e32 v156, v184, v208
	ds_read_b128 v[144:147], v156 offset:224
	ds_read_b128 v[148:151], v156 offset:192
	ds_read_b128 v[152:155], v156 offset:160
	ds_read_b128 v[156:159], v156 offset:128
	s_waitcnt lgkmcnt(3)
	v_pk_mul_f32 v[12:13], v[12:13], v[144:145]
	s_waitcnt lgkmcnt(2)
	v_pk_mul_f32 v[8:9], v[8:9], v[148:149]
	s_waitcnt lgkmcnt(1)
	v_pk_mul_f32 v[4:5], v[4:5], v[152:153]
	v_pk_mul_f32 v[14:15], v[14:15], v[146:147]
	v_pk_mul_f32 v[10:11], v[10:11], v[150:151]
	v_pk_mul_f32 v[6:7], v[6:7], v[154:155]
	s_waitcnt lgkmcnt(0)
	v_pk_mul_f32 v[2:3], v[2:3], v[158:159]
	v_pk_mul_f32 v[0:1], v[0:1], v[156:157]
	v_pk_mul_f32 v[60:61], v[60:61], v[144:145]
	v_pk_mul_f32 v[56:57], v[56:57], v[148:149]
	v_pk_mul_f32 v[52:53], v[52:53], v[152:153]
	v_pk_mul_f32 v[62:63], v[62:63], v[146:147]
	v_pk_mul_f32 v[58:59], v[58:59], v[150:151]
	v_pk_mul_f32 v[54:55], v[54:55], v[154:155]
	v_pk_mul_f32 v[50:51], v[50:51], v[158:159]
	v_pk_mul_f32 v[48:49], v[48:49], v[156:157]
	v_pk_mul_f32 v[44:45], v[44:45], v[144:145]
	v_pk_mul_f32 v[40:41], v[40:41], v[148:149]
	v_pk_mul_f32 v[36:37], v[36:37], v[152:153]
	v_pk_mul_f32 v[46:47], v[46:47], v[146:147]
	v_pk_mul_f32 v[42:43], v[42:43], v[150:151]
	v_pk_mul_f32 v[38:39], v[38:39], v[154:155]
	v_pk_mul_f32 v[34:35], v[34:35], v[158:159]
	v_pk_mul_f32 v[32:33], v[32:33], v[156:157]
	v_pk_mul_f32 v[28:29], v[28:29], v[144:145]
	v_pk_mul_f32 v[24:25], v[24:25], v[148:149]
	v_pk_mul_f32 v[20:21], v[20:21], v[152:153]
	v_pk_mul_f32 v[30:31], v[30:31], v[146:147]
	v_pk_mul_f32 v[26:27], v[26:27], v[150:151]
	v_pk_mul_f32 v[22:23], v[22:23], v[154:155]
	v_pk_mul_f32 v[18:19], v[18:19], v[158:159]
	v_pk_mul_f32 v[16:17], v[16:17], v[156:157]
; __device__ __forceinline__ void partialSM(f32x16& p0, f32x16& p1, float& m_reg, float& mn, float& alpha) {
;   constexpr float C = SCALE * 1.4426950408889634f;
;   float pmax = p0[0]; for (int r = 1; r < 16; ++r) pmax = fmaxf(pmax, p0[r]); for (int r = 0; r < 16; ++r) pmax = fmaxf(pmax, p1[r]);
;   { auto rr = __builtin_amdgcn_permlane32_swap(__float_as_uint(pmax), __float_as_uint(pmax), false, false);
;     pmax = fmaxf(__uint_as_float(rr[0]), __uint_as_float(rr[1])); }
;   if (__builtin_expect(__all(pmax - m_reg <= THR / SCALE), 1)) { mn = m_reg; alpha = 1.f; }
;   else { mn = fmaxf(m_reg, pmax); alpha = __builtin_amdgcn_exp2f((m_reg - mn) * C); m_reg = mn; }
;   float mnC = -mn * C;
;   for (int r = 0; r < 16; ++r) p0[r] = fmaf(p0[r], C, mnC); for (int r = 0; r < 16; ++r) p1[r] = fmaf(p1[r], C, mnC);
;   for (int r = 0; r < 16; ++r) p0[r] = __builtin_amdgcn_exp2f(p0[r]);
; }
; __device__ __forceinline__ void finishSM(f32x16& p0, f32x16& p1, float alpha, float& l_reg, bf16x8& pa0, bf16x8& pa1, bf16x8& pa2, bf16x8& pa3) {
;   for (int r = 0; r < 16; ++r) p1[r] = __builtin_amdgcn_exp2f(p1[r]);
;   float ps = 0; for (int r = 0; r < 16; ++r) ps += p0[r]; for (int r = 0; r < 16; ++r) ps += p1[r];
;   { auto rr = __builtin_amdgcn_permlane32_swap(__float_as_uint(ps), __float_as_uint(ps), false, false);
;     ps = __uint_as_float(rr[0]) + __uint_as_float(rr[1]); }
;   l_reg = l_reg * alpha + ps;
;     ...
;   PK4(p0, 0, pa0); PK4(p0, 8, pa1); PK4(p1, 0, pa2); PK4(p1, 8, pa3);
;     ...
; }
; __device__ __forceinline__ void qkt(f32x16& p0, f32x16& p1, const bf16* Ks, const bf16x8* qr, int r32, int hi) {
;   p0 = f32x16{}; p1 = f32x16{};
;   for (int d0 = 0; d0 < 8; ++d0) { int cb = (d0 * 16 + hi * 8) * 2;
;     bf16x8 b0 = *reinterpret_cast<const bf16x8*>((const char*)Ks + KSWZ(r32, cb));
; template <typename TQ>
; __device__ __forceinline__ void attn_dense_body(const TQ* __restrict__ Qb, const bf16* __restrict__ Kh, const bf16* __restrict__ Vh,
;                                                 unsigned short* __restrict__ Ob, int seq, char* lds) {
;     ...
;     pv_d0(o, vb0 + (int)SHM_V, pa0, pa1, pa2, pa3); partialSM(pA0, pA1, m_reg, mnA, alA);
;     __syncthreads(); SWAIT(); SWRITE(1, SO);
;     RESC(alA); __syncthreads();
;   }
;   SBAR(); qkt(pB0, pB1, (bf16*)((char*)K_lds + SHM_K), qr, r32, hi);
;   finishSM(pA0, pA1, alA, l_reg, pa0, pa1, pa2, pa3); SBAR();
.LBB0_86:
	v_cndmask_b32_e64 v168, v161, v205, s[0:1]
	v_mul_f32_e32 v144, 0xbe0293ee, v168
	v_mov_b32_e32 v145, v144
	v_fmamk_f32 v80, v80, 0x3e0293ee, v144
	v_fmamk_f32 v81, v81, 0x3e0293ee, v144
	v_fmamk_f32 v82, v82, 0x3e0293ee, v144
	v_fmamk_f32 v83, v83, 0x3e0293ee, v144
	v_fmamk_f32 v84, v84, 0x3e0293ee, v144
	v_fmamk_f32 v85, v85, 0x3e0293ee, v144
	v_fmamk_f32 v86, v86, 0x3e0293ee, v144
	v_fmamk_f32 v87, v87, 0x3e0293ee, v144
	v_fmamk_f32 v88, v88, 0x3e0293ee, v144
	v_fmamk_f32 v89, v89, 0x3e0293ee, v144
	v_fmamk_f32 v90, v90, 0x3e0293ee, v144
	v_fmamk_f32 v91, v91, 0x3e0293ee, v144
	v_fmamk_f32 v92, v92, 0x3e0293ee, v144
	v_fmamk_f32 v93, v93, 0x3e0293ee, v144
	v_fmamk_f32 v94, v94, 0x3e0293ee, v144
	v_fmac_f32_e32 v145, 0x3e0293ee, v95
	v_exp_f32_e32 v161, v80
	v_exp_f32_e32 v175, v81
	v_exp_f32_e32 v162, v82
	v_exp_f32_e32 v205, v83
	v_exp_f32_e32 v174, v84
	v_exp_f32_e32 v214, v85
	v_exp_f32_e32 v163, v86
	v_exp_f32_e32 v173, v87
	v_exp_f32_e32 v164, v88
	v_exp_f32_e32 v171, v89
	v_exp_f32_e32 v165, v90
	v_exp_f32_e32 v172, v91
	v_exp_f32_e32 v166, v92
	v_exp_f32_e32 v169, v93
	v_exp_f32_e32 v167, v94
	v_exp_f32_e32 v170, v145
	v_pk_fma_f32 v[158:159], v[64:65], s[22:23], v[144:145] op_sel_hi:[1,0,0]
	v_add_f32_e32 v64, v202, v203
	v_fmac_f32_e32 v64, v201, v186
	v_add_f32_e32 v186, v206, v207
	s_mov_b64 s[0:1], 0x8000
	v_pk_fma_f32 v[156:157], v[66:67], s[22:23], v[144:145] op_sel_hi:[1,0,0]
	v_pk_fma_f32 v[152:153], v[68:69], s[22:23], v[144:145] op_sel_hi:[1,0,0]
	v_pk_fma_f32 v[148:149], v[70:71], s[22:23], v[144:145] op_sel_hi:[1,0,0]
	v_pk_fma_f32 v[146:147], v[72:73], s[22:23], v[144:145] op_sel_hi:[1,0,0]
	v_pk_fma_f32 v[154:155], v[74:75], s[22:23], v[144:145] op_sel_hi:[1,0,0]
	v_pk_fma_f32 v[150:151], v[76:77], s[22:23], v[144:145] op_sel_hi:[1,0,0]
	v_pk_fma_f32 v[144:145], v[78:79], s[22:23], v[144:145] op_sel_hi:[1,0,0]
	v_fmac_f32_e32 v186, v64, v204
	s_add_i32 s2, s2, 2
	v_lshl_add_u64 v[180:181], v[180:181], 0, s[0:1]
	s_and_b64 vcc, exec, s[42:43]
	s_waitcnt lgkmcnt(0)
	s_waitcnt vmcnt(4)
	s_barrier
	s_cbranch_vccnz .LBB0_88
	v_mov_b32_e32 v201, v160
	s_branch .LBB0_76
.LBB0_88:
	ds_read_b128 v[64:67], v193 offset:49152
	ds_read_b128 v[68:71], v193 offset:57344
	s_waitcnt lgkmcnt(1)
	v_mfma_f32_32x32x16_bf16 v[80:95], v[64:67], v[112:115], 0
	s_waitcnt lgkmcnt(0)
	v_mfma_f32_32x32x16_bf16 v[64:79], v[68:71], v[112:115], 0
	ds_read_b128 v[112:115], v198 offset:49152
	ds_read_b128 v[128:131], v198 offset:57344
	s_waitcnt lgkmcnt(1)
	v_mfma_f32_32x32x16_bf16 v[80:95], v[112:115], v[108:111], v[80:95]
	s_waitcnt lgkmcnt(0)
	v_mfma_f32_32x32x16_bf16 v[64:79], v[128:131], v[108:111], v[64:79]
	ds_read_b128 v[108:111], v197 offset:49152
	ds_read_b128 v[112:115], v197 offset:57344
	s_waitcnt lgkmcnt(1)
	v_mfma_f32_32x32x16_bf16 v[80:95], v[108:111], v[120:123], v[80:95]
	s_waitcnt lgkmcnt(0)
	v_mfma_f32_32x32x16_bf16 v[64:79], v[112:115], v[120:123], v[64:79]
	ds_read_b128 v[108:111], v196 offset:49152
	ds_read_b128 v[112:115], v196 offset:57344
	v_exp_f32_e32 v120, v144
	v_exp_f32_e32 v121, v145
	s_waitcnt lgkmcnt(1)
	v_mfma_f32_32x32x16_bf16 v[80:95], v[108:111], v[124:127], v[80:95]
	s_waitcnt lgkmcnt(0)
	v_mfma_f32_32x32x16_bf16 v[64:79], v[112:115], v[124:127], v[64:79]
	ds_read_b128 v[108:111], v194 offset:49152
	ds_read_b128 v[112:115], v194 offset:57344
	s_waitcnt lgkmcnt(1)
	v_mfma_f32_32x32x16_bf16 v[80:95], v[108:111], v[116:119], v[80:95]
	s_waitcnt lgkmcnt(0)
	v_mfma_f32_32x32x16_bf16 v[64:79], v[112:115], v[116:119], v[64:79]
	ds_read_b128 v[108:111], v195 offset:49152
	ds_read_b128 v[112:115], v195 offset:57344
	v_exp_f32_e32 v116, v154
	v_exp_f32_e32 v117, v155
	v_exp_f32_e32 v118, v150
	v_exp_f32_e32 v119, v151
	s_waitcnt lgkmcnt(1)
	v_mfma_f32_32x32x16_bf16 v[80:95], v[108:111], v[104:107], v[80:95]
	s_waitcnt lgkmcnt(0)
	v_mfma_f32_32x32x16_bf16 v[64:79], v[112:115], v[104:107], v[64:79]
	ds_read_b128 v[104:107], v200 offset:49152
	ds_read_b128 v[108:111], v200 offset:57344
	v_exp_f32_e32 v112, v148
	v_exp_f32_e32 v113, v149
	v_exp_f32_e32 v114, v146
	v_exp_f32_e32 v115, v147
	s_waitcnt lgkmcnt(1)
	v_mfma_f32_32x32x16_bf16 v[80:95], v[104:107], v[100:103], v[80:95]
	s_waitcnt lgkmcnt(0)
	v_mfma_f32_32x32x16_bf16 v[64:79], v[108:111], v[100:103], v[64:79]
	ds_read_b128 v[100:103], v199 offset:49152
	ds_read_b128 v[104:107], v199 offset:57344
	v_exp_f32_e32 v108, v156
	v_exp_f32_e32 v109, v157
	v_exp_f32_e32 v110, v152
	v_exp_f32_e32 v111, v153
	s_waitcnt lgkmcnt(1)
	v_mfma_f32_32x32x16_bf16 v[80:95], v[100:103], v[96:99], v[80:95]
	s_waitcnt lgkmcnt(0)
; #define SBAR() __builtin_amdgcn_sched_barrier(0)
; __device__ __forceinline__ void finishSM(f32x16& p0, f32x16& p1, float alpha, float& l_reg, bf16x8& pa0, bf16x8& pa1, bf16x8& pa2, bf16x8& pa3) {
;   for (int r = 0; r < 16; ++r) p1[r] = __builtin_amdgcn_exp2f(p1[r]);
;   float ps = 0; for (int r = 0; r < 16; ++r) ps += p0[r]; for (int r = 0; r < 16; ++r) ps += p1[r];
;   { auto rr = __builtin_amdgcn_permlane32_swap(__float_as_uint(ps), __float_as_uint(ps), false, false);
;     ps = __uint_as_float(rr[0]) + __uint_as_float(rr[1]); }
;   l_reg = l_reg * alpha + ps;
;     ...
;   PK4(p0, 0, pa0); PK4(p0, 8, pa1); PK4(p1, 0, pa2); PK4(p1, 8, pa3);
;     ...
; }
; __device__ __forceinline__ void qkt(f32x16& p0, f32x16& p1, const bf16* Ks, const bf16x8* qr, int r32, int hi) {
;   p0 = f32x16{}; p1 = f32x16{};
;   for (int d0 = 0; d0 < 8; ++d0) { int cb = (d0 * 16 + hi * 8) * 2;
;     bf16x8 b0 = *reinterpret_cast<const bf16x8*>((const char*)Ks + KSWZ(r32, cb));
;     bf16x8 b1 = *reinterpret_cast<const bf16x8*>((const char*)Ks + KSWZ(32 + r32, cb));
;     p0 = __builtin_amdgcn_mfma_f32_32x32x16_bf16(b0, qr[d0], p0, 0, 0, 0);
;     p1 = __builtin_amdgcn_mfma_f32_32x32x16_bf16(b1, qr[d0], p1, 0, 0, 0); }
; }
; __device__ __forceinline__ int v_st(int k, int c) { const int kk = (k & ~0xC) | ((k & 4) << 1) | ((k & 8) >> 1); return ((kk >> 3) * 4 + (c >> 5)) * 512 + ((kk & 7) * 32 + (c & 31)) * 2; }
; __device__ __forceinline__ int v_rd_base(int lane) { return ((lane & 3) << 3) | (((lane >> 2) & 3) << 6) | (((lane >> 4) & 1) << 5) | (((lane >> 5) & 1) << 8); }
; template <int OFF> __device__ __forceinline__ s16x4 tr_read(int vb) {
;   s16x4 r; asm volatile("ds_read_b64_tr_b16 %0, %1 offset:%2" : "=&v"(r) : "v"(vb), "i"(OFF) : "memory"); return r;
; }
; template <int D0> __device__ __forceinline__ void pv_one(f32x16& od, int vb, bf16x8 pa0, bf16x8 pa1, bf16x8 pa2, bf16x8 pa3) {
; template <typename TQ>
; __device__ __forceinline__ void attn_dense_body(const TQ* __restrict__ Qb, const bf16* __restrict__ Kh, const bf16* __restrict__ Vh,
;                                                 unsigned short* __restrict__ Ob, int seq, char* lds) {
;     ...
;   finishSM(pA0, pA1, alA, l_reg, pa0, pa1, pa2, pa3); SBAR();
;   pv_d0(o, vb0, pa0, pa1, pa2, pa3); partialSM(pB0, pB1, m_reg, mnB, alB);
;   __syncthreads(); RESC(alB);
	v_mfma_f32_32x32x16_bf16 v[64:79], v[104:107], v[96:99], v[64:79]
	v_add_f32_e32 v96, 0, v161
	v_add_f32_e32 v96, v175, v96
	v_add_f32_e32 v96, v162, v96
	v_add_f32_e32 v96, v205, v96
	v_add_f32_e32 v96, v174, v96
	v_add_f32_e32 v96, v214, v96
	v_add_f32_e32 v96, v163, v96
	v_add_f32_e32 v96, v173, v96
	v_add_f32_e32 v96, v164, v96
	v_add_f32_e32 v96, v171, v96
	v_add_f32_e32 v96, v165, v96
	v_add_f32_e32 v96, v172, v96
	v_exp_f32_e32 v106, v158
	v_add_f32_e32 v96, v166, v96
	v_exp_f32_e32 v107, v159
	v_add_f32_e32 v96, v169, v96
	v_add_f32_e32 v96, v167, v96
	v_add_f32_e32 v96, v170, v96
	v_add_f32_e32 v96, v106, v96
	v_add_f32_e32 v96, v107, v96
	v_add_f32_e32 v96, v108, v96
	v_add_f32_e32 v96, v109, v96
	v_add_f32_e32 v96, v110, v96
	v_add_f32_e32 v96, v111, v96
	v_add_f32_e32 v96, v112, v96
	v_add_f32_e32 v96, v113, v96
	v_add_f32_e32 v96, v114, v96
	v_add_f32_e32 v96, v115, v96
	v_add_f32_e32 v96, v116, v96
	v_add_f32_e32 v96, v117, v96
	v_add_f32_e32 v96, v118, v96
	v_add_f32_e32 v96, v119, v96
	v_add_f32_e32 v96, v120, v96
	v_add_f32_e32 v100, v121, v96
	v_mov_b32_e32 v101, v100
	v_cvt_pk_bf16_f32 v96, v161, v175
	v_cvt_pk_bf16_f32 v97, v162, v205
	v_cvt_pk_bf16_f32 v98, v174, v214
	v_cvt_pk_bf16_f32 v99, v163, v173
	s_nop 1
	v_permlane32_swap_b32_e32 v100, v101
	v_permlane32_swap_b32_e32 v96, v98
	v_permlane32_swap_b32_e32 v97, v99
	v_cvt_pk_bf16_f32 v102, v164, v171
	v_cvt_pk_bf16_f32 v103, v165, v172
	v_cvt_pk_bf16_f32 v104, v166, v169
	v_cvt_pk_bf16_f32 v105, v167, v170
	v_cvt_pk_bf16_f32 v106, v106, v107
	v_cvt_pk_bf16_f32 v107, v108, v109
	v_cvt_pk_bf16_f32 v108, v110, v111
	v_cvt_pk_bf16_f32 v109, v112, v113
	v_cvt_pk_bf16_f32 v110, v114, v115
	v_cvt_pk_bf16_f32 v111, v116, v117
	v_cvt_pk_bf16_f32 v112, v118, v119
	v_cvt_pk_bf16_f32 v113, v120, v121
	s_nop 0
	v_permlane32_swap_b32_e32 v102, v104
	v_permlane32_swap_b32_e32 v103, v105
	v_permlane32_swap_b32_e32 v106, v108
	v_permlane32_swap_b32_e32 v107, v109
	v_permlane32_swap_b32_e32 v110, v112
	v_permlane32_swap_b32_e32 v111, v113
	ds_read_b64_tr_b16 v[114:115], v188 offset:0
	ds_read_b64_tr_b16 v[116:117], v188 offset:0x800
	ds_read_b64_tr_b16 v[118:119], v188 offset:0x1000
	ds_read_b64_tr_b16 v[120:121], v188 offset:0x1800
	ds_read_b64_tr_b16 v[122:123], v188 offset:0x2000
	ds_read_b64_tr_b16 v[124:125], v188 offset:0x2800
	ds_read_b64_tr_b16 v[126:127], v188 offset:0x3000
	ds_read_b64_tr_b16 v[128:129], v188 offset:0x3800
	s_waitcnt lgkmcnt(0)
	s_nop 0
	v_mfma_f32_32x32x16_bf16 v[0:15], v[96:99], v[114:117], v[0:15]
	ds_read_b64_tr_b16 v[114:115], v188 offset:0x200
	ds_read_b64_tr_b16 v[116:117], v188 offset:0xa00
	v_mfma_f32_32x32x16_bf16 v[0:15], v[102:105], v[118:121], v[0:15]
	ds_read_b64_tr_b16 v[118:119], v188 offset:0x1200
	ds_read_b64_tr_b16 v[120:121], v188 offset:0x1a00
	v_mfma_f32_32x32x16_bf16 v[0:15], v[106:109], v[122:125], v[0:15]
	ds_read_b64_tr_b16 v[122:123], v188 offset:0x2200
	ds_read_b64_tr_b16 v[124:125], v188 offset:0x2a00
	v_mfma_f32_32x32x16_bf16 v[0:15], v[110:113], v[126:129], v[0:15]
	ds_read_b64_tr_b16 v[126:127], v188 offset:0x3200
	ds_read_b64_tr_b16 v[128:129], v188 offset:0x3a00
	s_waitcnt lgkmcnt(0)
	v_mfma_f32_32x32x16_bf16 v[48:63], v[96:99], v[114:117], v[48:63]
	ds_read_b64_tr_b16 v[114:115], v188 offset:0x400
	ds_read_b64_tr_b16 v[116:117], v188 offset:0xc00
	v_mfma_f32_32x32x16_bf16 v[48:63], v[102:105], v[118:121], v[48:63]
	ds_read_b64_tr_b16 v[118:119], v188 offset:0x1400
	ds_read_b64_tr_b16 v[120:121], v188 offset:0x1c00
	v_mfma_f32_32x32x16_bf16 v[48:63], v[106:109], v[122:125], v[48:63]
	ds_read_b64_tr_b16 v[122:123], v188 offset:0x2400
	ds_read_b64_tr_b16 v[124:125], v188 offset:0x2c00
	v_mfma_f32_32x32x16_bf16 v[48:63], v[110:113], v[126:129], v[48:63]
	ds_read_b64_tr_b16 v[126:127], v188 offset:0x3400
	ds_read_b64_tr_b16 v[128:129], v188 offset:0x3c00
	s_waitcnt lgkmcnt(0)
	v_mfma_f32_32x32x16_bf16 v[32:47], v[96:99], v[114:117], v[32:47]
	ds_read_b64_tr_b16 v[114:115], v188 offset:0x600
	ds_read_b64_tr_b16 v[116:117], v188 offset:0xe00
	v_mfma_f32_32x32x16_bf16 v[32:47], v[102:105], v[118:121], v[32:47]
	ds_read_b64_tr_b16 v[118:119], v188 offset:0x1600
	ds_read_b64_tr_b16 v[120:121], v188 offset:0x1e00
	v_mfma_f32_32x32x16_bf16 v[32:47], v[106:109], v[122:125], v[32:47]
	ds_read_b64_tr_b16 v[122:123], v188 offset:0x2600
	ds_read_b64_tr_b16 v[124:125], v188 offset:0x2e00
	v_mfma_f32_32x32x16_bf16 v[32:47], v[110:113], v[126:129], v[32:47]
	ds_read_b64_tr_b16 v[126:127], v188 offset:0x3600
	ds_read_b64_tr_b16 v[128:129], v188 offset:0x3e00
	s_waitcnt lgkmcnt(0)
	v_mfma_f32_32x32x16_bf16 v[16:31], v[96:99], v[114:117], v[16:31]
	v_max_f32_e32 v96, v81, v81
	v_max_f32_e32 v97, v80, v80
	v_max_f32_e32 v96, v97, v96
	v_max3_f32 v96, v96, v82, v83
	v_max3_f32 v96, v96, v84, v85
	v_max3_f32 v96, v96, v86, v87
	v_max3_f32 v96, v96, v88, v89
	v_max3_f32 v96, v96, v90, v91
	v_max3_f32 v96, v96, v92, v93
	v_mfma_f32_32x32x16_bf16 v[16:31], v[102:105], v[118:121], v[16:31]
	v_max3_f32 v96, v96, v94, v95
	v_max3_f32 v96, v96, v64, v65
	v_max3_f32 v96, v96, v66, v67
	v_max3_f32 v96, v96, v68, v69
	v_max3_f32 v96, v96, v70, v71
	v_max3_f32 v96, v96, v72, v73
	v_max3_f32 v96, v96, v74, v75
	v_max3_f32 v96, v96, v76, v77
	v_mfma_f32_32x32x16_bf16 v[16:31], v[106:109], v[122:125], v[16:31]
	v_max3_f32 v96, v96, v78, v79
	v_mov_b32_e32 v97, v96
	s_nop 1
	v_permlane32_swap_b32_e32 v96, v97
	v_max_f32_e32 v97, v97, v97
	v_max_f32_e32 v96, v96, v96
	v_max_f32_e32 v96, v96, v97
	v_sub_f32_e32 v97, v96, v168
	v_cmp_ge_f32_e32 vcc, s4, v97
	v_max_f32_e32 v97, v168, v168
	v_max_f32_e32 v97, v97, v96
	v_mfma_f32_32x32x16_bf16 v[16:31], v[110:113], v[126:129], v[16:31]
	v_sub_f32_e32 v96, v168, v97
	v_mul_f32_e32 v96, 0x3e0293ee, v96
	v_exp_f32_e32 v96, v96
	s_cmp_eq_u64 vcc, exec
	s_cselect_b64 s[0:1], -1, 0
	v_cndmask_b32_e64 v96, v96, 1.0, s[0:1]
	v_cmp_gt_f32_e32 vcc, 1.0, v96
	s_waitcnt vmcnt(0)
	s_barrier
; #define SBAR() __builtin_amdgcn_sched_barrier(0)
; #define RESC(a) do { if (__any((a) < 1.f)) { if (hi == 0) al_l[r32] = (a); asm volatile("s_waitcnt lgkmcnt(0)" ::: "memory"); \
;     for (int d = 0; d < 4; ++d) for (int r = 0; r < 16; ++r) o[d][r] *= al_l[crow(r, hi)]; } } while (0)
; template <typename TQ>
; __device__ __forceinline__ void attn_dense_body(const TQ* __restrict__ Qb, const bf16* __restrict__ Kh, const bf16* __restrict__ Vh,
;                                                 unsigned short* __restrict__ Ob, int seq, char* lds) {
;     ...
;   __syncthreads(); RESC(alB);
;   finishSM(pB0, pB1, alB, l_reg, pa0, pa1, pa2, pa3); SBAR();
	s_cbranch_vccz .LBB0_92
	s_mov_b64 s[42:43], exec
	s_and_b64 s[28:29], s[42:43], s[38:39]
	v_mov_b64_e32 v[228:229], v[242:243]
	v_mov_b64_e32 v[230:231], v[218:219]
	s_mov_b64 exec, s[28:29]
	ds_write_b32 v185, v96 offset:128
	s_or_b64 exec, exec, s[42:43]
	s_waitcnt lgkmcnt(0)
	v_add_u32_e32 v98, v184, v208
	ds_read_b128 v[102:105], v98 offset:224
	ds_read_b128 v[106:109], v98 offset:192
	ds_read_b128 v[110:113], v98 offset:160
	ds_read_b128 v[114:117], v98 offset:128
	s_waitcnt lgkmcnt(3)
	v_pk_mul_f32 v[12:13], v[12:13], v[102:103]
	s_waitcnt lgkmcnt(2)
	v_pk_mul_f32 v[8:9], v[8:9], v[106:107]
	s_waitcnt lgkmcnt(1)
	v_pk_mul_f32 v[4:5], v[4:5], v[110:111]
	v_pk_mul_f32 v[14:15], v[14:15], v[104:105]
	v_pk_mul_f32 v[10:11], v[10:11], v[108:109]
	v_pk_mul_f32 v[6:7], v[6:7], v[112:113]
	s_waitcnt lgkmcnt(0)
	v_pk_mul_f32 v[2:3], v[2:3], v[116:117]
	v_pk_mul_f32 v[0:1], v[0:1], v[114:115]
	v_pk_mul_f32 v[60:61], v[60:61], v[102:103]
	v_pk_mul_f32 v[56:57], v[56:57], v[106:107]
	v_pk_mul_f32 v[52:53], v[52:53], v[110:111]
	v_pk_mul_f32 v[62:63], v[62:63], v[104:105]
	v_pk_mul_f32 v[58:59], v[58:59], v[108:109]
	v_pk_mul_f32 v[54:55], v[54:55], v[112:113]
	v_pk_mul_f32 v[50:51], v[50:51], v[116:117]
	v_pk_mul_f32 v[48:49], v[48:49], v[114:115]
	v_pk_mul_f32 v[44:45], v[44:45], v[102:103]
	v_pk_mul_f32 v[40:41], v[40:41], v[106:107]
	v_pk_mul_f32 v[36:37], v[36:37], v[110:111]
	v_pk_mul_f32 v[46:47], v[46:47], v[104:105]
	v_pk_mul_f32 v[42:43], v[42:43], v[108:109]
	v_pk_mul_f32 v[38:39], v[38:39], v[112:113]
	v_pk_mul_f32 v[34:35], v[34:35], v[116:117]
	v_pk_mul_f32 v[32:33], v[32:33], v[114:115]
	v_pk_mul_f32 v[28:29], v[28:29], v[102:103]
	v_pk_mul_f32 v[24:25], v[24:25], v[106:107]
	v_pk_mul_f32 v[20:21], v[20:21], v[110:111]
	v_pk_mul_f32 v[30:31], v[30:31], v[104:105]
	v_pk_mul_f32 v[26:27], v[26:27], v[108:109]
	v_pk_mul_f32 v[22:23], v[22:23], v[112:113]
	v_pk_mul_f32 v[18:19], v[18:19], v[116:117]
	v_pk_mul_f32 v[16:17], v[16:17], v[114:115]
	s_branch .LBB0_93
